# mixer output sections: per-head norm gain loaded once instead of reloaded+waited after every store (HGRN2 and GLA, 6 sites)
# baseline (speedup 1.0000x reference)
.LBB0_783:
	s_or_b64 exec, exec, s[6:7]
	s_add_i32 s2, s50, s22
	s_lshl_b32 s6, s8, 2
	s_add_u32 s6, s38, s6
	s_addc_u32 s7, s39, 0
	s_waitcnt lgkmcnt(0)
	v_lshl_add_u64 v[76:77], v[74:75], 2, s[6:7]
	s_barrier
	global_load_dwordx4 v[240:243], v[76:77], off
	v_ashrrev_i32_e32 v95, 31, v94
	v_lshl_add_u32 v1, v144, 2, s96
	v_lshlrev_b64 v[96:97], 11, v[2:3]
	v_lshl_add_u32 v2, v73, 2, s96
	s_waitcnt vmcnt(4)
	v_lshlrev_b32_e32 v98, 16, v80
	v_and_b32_e32 v99, 0xffff0000, v80
	v_lshlrev_b32_e32 v100, 16, v81
	v_and_b32_e32 v101, 0xffff0000, v81
	ds_read2st64_b32 v[102:103], v1 offset1:1
	ds_read2st64_b32 v[104:105], v1 offset0:2 offset1:3
	ds_read2st64_b32 v[106:107], v1 offset0:4 offset1:5
	ds_read2st64_b32 v[108:109], v1 offset0:6 offset1:7
	v_lshlrev_b64 v[80:81], 1, v[94:95]
	ds_read2st64_b32 v[94:95], v2 offset1:1
	ds_read2st64_b32 v[110:111], v2 offset0:2 offset1:3
	ds_read2st64_b32 v[112:113], v2 offset0:4 offset1:5
	ds_read2st64_b32 v[114:115], v2 offset0:6 offset1:7
	s_waitcnt lgkmcnt(7)
	v_mov_b32_e32 v117, v102
	s_waitcnt lgkmcnt(3)
	v_mov_b32_e32 v116, v94
	v_mov_b32_e32 v102, v95
	v_pk_add_f32 v[116:117], v[116:117], 0 op_sel_hi:[1,0]
	s_waitcnt lgkmcnt(2)
	v_mov_b32_e32 v94, v110
	v_mov_b32_e32 v95, v104
	v_pk_add_f32 v[102:103], v[116:117], v[102:103]
	v_mov_b32_e32 v104, v111
	v_pk_add_f32 v[94:95], v[102:103], v[94:95]
	v_mul_f32_e32 v1, 0xbfb8aa3b, v98
	s_waitcnt lgkmcnt(1)
	v_mov_b32_e32 v110, v112
	v_mov_b32_e32 v111, v106
	v_pk_add_f32 v[94:95], v[94:95], v[104:105]
	v_exp_f32_e32 v1, v1
	v_mov_b32_e32 v106, v113
	v_pk_add_f32 v[94:95], v[94:95], v[110:111]
	s_waitcnt lgkmcnt(0)
	v_mov_b32_e32 v112, v114
	v_mov_b32_e32 v113, v108
	v_pk_add_f32 v[94:95], v[94:95], v[106:107]
	v_mov_b32_e32 v108, v115
	v_pk_add_f32 v[94:95], v[94:95], v[112:113]
	v_mov_b64_e32 v[86:87], s[82:83]
	v_pk_add_f32 v[94:95], v[94:95], v[108:109]
	v_mul_f32_e32 v61, 0xbfb8aa3b, v99
	v_mul_f32_e32 v73, 0xbfb8aa3b, v100
	v_mul_f32_e32 v83, 0xbfb8aa3b, v101
	v_add_f32_e32 v1, 1.0, v1
	v_pk_fma_f32 v[94:95], v[94:95], s[80:81], v[86:87] op_sel_hi:[1,0,0]
	v_exp_f32_e32 v2, v61
	v_exp_f32_e32 v61, v73
	v_exp_f32_e32 v73, v83
	v_rcp_f32_e32 v114, v1
	v_mul_f32_e32 v1, 0x4b800000, v95
	v_cmp_gt_f32_e32 vcc, s42, v95
	v_add_f32_e32 v2, 1.0, v2
	v_add_f32_e32 v61, 1.0, v61
	v_cndmask_b32_e32 v1, v95, v1, vcc
	v_rsq_f32_e32 v1, v1
	v_add_f32_e32 v73, 1.0, v73
	v_rcp_f32_e32 v115, v2
	v_rcp_f32_e32 v118, v61
	v_rcp_f32_e32 v119, v73
	v_mul_f32_e32 v2, 0x45800000, v1
	v_cndmask_b32_e32 v2, v1, v2, vcc
	v_lshl_add_u64 v[96:97], s[16:17], 0, v[96:97]
	v_pk_mul_f32 v[68:69], v[68:69], v[2:3] op_sel_hi:[1,0]
	v_pk_mul_f32 v[70:71], v[70:71], v[2:3] op_sel_hi:[1,0]
	v_lshl_add_u64 v[96:97], v[96:97], 0, s[62:63]
	v_pk_mul_f32 v[98:99], v[114:115], v[98:99]
	v_pk_mul_f32 v[100:101], v[118:119], v[100:101]
	v_lshlrev_b32_e32 v74, 1, v150
	v_mov_b32_e32 v75, v0
	v_lshl_add_u64 v[96:97], v[96:97], 0, v[80:81]
	v_lshl_add_u64 v[96:97], v[96:97], 0, v[74:75]
	v_cmp_gt_f32_e32 vcc, s42, v94
	v_mov_b32_e32 v83, v3
	v_lshlrev_b64 v[82:83], 11, v[82:83]
	v_lshl_add_u64 v[82:83], s[16:17], 0, v[82:83]
	v_lshl_add_u64 v[82:83], v[82:83], 0, s[62:63]
	v_lshl_add_u64 v[82:83], v[82:83], 0, v[80:81]
	v_lshl_add_u64 v[82:83], v[82:83], 0, v[74:75]
	s_add_i32 s73, s73, s88
	s_add_i32 s61, s61, s91
	s_cmpk_gt_i32 s2, 0x7ff
	s_cselect_b64 s[6:7], -1, 0
	s_waitcnt vmcnt(0)
	v_pk_mul_f32 v[68:69], v[240:241], v[68:69]
	v_pk_mul_f32 v[70:71], v[242:243], v[70:71]
	v_pk_mul_f32 v[68:69], v[98:99], v[68:69]
	v_pk_mul_f32 v[70:71], v[100:101], v[70:71]
	v_cvt_pk_bf16_f32 v68, v68, v69
	v_cvt_pk_bf16_f32 v69, v70, v71
	global_store_dwordx2 v[96:97], v[68:69], off offset:1024
	s_nop 0
	v_lshlrev_b32_e32 v90, 16, v84
	v_mul_f32_e32 v1, 0xbfb8aa3b, v90
	v_exp_f32_e32 v1, v1
	v_and_b32_e32 v91, 0xffff0000, v84
	v_lshlrev_b32_e32 v84, 16, v85
	v_and_b32_e32 v85, 0xffff0000, v85
	v_mul_f32_e32 v2, 0xbfb8aa3b, v91
	v_mul_f32_e32 v61, 0xbfb8aa3b, v84
	v_mul_f32_e32 v73, 0xbfb8aa3b, v85
	v_add_f32_e32 v1, 1.0, v1
	v_exp_f32_e32 v2, v2
	v_exp_f32_e32 v61, v61
	v_exp_f32_e32 v73, v73
	v_rcp_f32_e32 v92, v1
	v_mul_f32_e32 v1, 0x4b800000, v94
	v_cndmask_b32_e32 v1, v94, v1, vcc
	v_rsq_f32_e32 v1, v1
	v_add_f32_e32 v2, 1.0, v2
	v_add_f32_e32 v61, 1.0, v61
	v_add_f32_e32 v73, 1.0, v73
	v_rcp_f32_e32 v93, v2
	v_rcp_f32_e32 v96, v61
	v_rcp_f32_e32 v97, v73
	v_mul_f32_e32 v2, 0x45800000, v1
	v_cndmask_b32_e32 v2, v1, v2, vcc
	v_pk_mul_f32 v[64:65], v[64:65], v[2:3] op_sel_hi:[1,0]
	v_pk_mul_f32 v[66:67], v[66:67], v[2:3] op_sel_hi:[1,0]
	v_pk_mul_f32 v[90:91], v[92:93], v[90:91]
	v_pk_mul_f32 v[84:85], v[96:97], v[84:85]
	v_lshl_add_u32 v1, v89, 2, s96
	v_lshl_add_u32 v2, v88, 2, s96
	v_mov_b32_e32 v73, v3
	v_lshlrev_b64 v[72:73], 11, v[72:73]
	v_lshl_add_u64 v[72:73], s[16:17], 0, v[72:73]
	v_lshl_add_u64 v[72:73], v[72:73], 0, s[62:63]
	v_lshl_add_u64 v[72:73], v[72:73], 0, v[80:81]
	v_lshl_add_u64 v[72:73], v[72:73], 0, v[74:75]
	s_nop 0
	v_pk_mul_f32 v[64:65], v[240:241], v[64:65]
	v_pk_mul_f32 v[66:67], v[242:243], v[66:67]
	v_pk_mul_f32 v[64:65], v[90:91], v[64:65]
	v_pk_mul_f32 v[66:67], v[84:85], v[66:67]
	v_cvt_pk_bf16_f32 v64, v64, v65
	v_cvt_pk_bf16_f32 v65, v66, v67
	global_store_dwordx2 v[82:83], v[64:65], off offset:1024
	s_nop 0
	v_and_b32_e32 v69, 0xffff0000, v78
	v_lshlrev_b32_e32 v70, 16, v79
	v_and_b32_e32 v71, 0xffff0000, v79
	v_mul_f32_e32 v61, 0xbfb8aa3b, v69
	v_mul_f32_e32 v98, 0xbfb8aa3b, v70
	v_mul_f32_e32 v99, 0xbfb8aa3b, v71
	v_lshlrev_b32_e32 v68, 16, v78
	ds_read2st64_b32 v[78:79], v1 offset1:1
	ds_read2st64_b32 v[82:83], v1 offset0:2 offset1:3
	ds_read2st64_b32 v[84:85], v1 offset0:4 offset1:5
	ds_read2st64_b32 v[88:89], v1 offset0:6 offset1:7
	ds_read2st64_b32 v[90:91], v2 offset1:1
	ds_read2st64_b32 v[92:93], v2 offset0:2 offset1:3
	ds_read2st64_b32 v[94:95], v2 offset0:4 offset1:5
	ds_read2st64_b32 v[96:97], v2 offset0:6 offset1:7
	v_exp_f32_e32 v2, v61
	v_exp_f32_e32 v61, v98
	v_exp_f32_e32 v98, v99
	s_waitcnt lgkmcnt(7)
	v_mov_b32_e32 v99, v78
	s_waitcnt lgkmcnt(3)
	v_mov_b32_e32 v78, v91
	v_mov_b32_e32 v91, v82
	v_add_f32_e32 v101, 1.0, v98
	v_mov_b32_e32 v98, v90
	v_pk_add_f32 v[98:99], v[98:99], 0 op_sel_hi:[1,0]
	s_waitcnt lgkmcnt(2)
	v_mov_b32_e32 v90, v92
	v_pk_add_f32 v[78:79], v[98:99], v[78:79]
	v_mov_b32_e32 v82, v93
	v_pk_add_f32 v[78:79], v[78:79], v[90:91]
	v_mul_f32_e32 v1, 0xbfb8aa3b, v68
	s_waitcnt lgkmcnt(1)
	v_mov_b32_e32 v92, v94
	v_mov_b32_e32 v93, v84
	v_pk_add_f32 v[78:79], v[78:79], v[82:83]
	v_exp_f32_e32 v1, v1
	v_mov_b32_e32 v84, v95
	v_pk_add_f32 v[78:79], v[78:79], v[92:93]
	s_waitcnt lgkmcnt(0)
	v_mov_b32_e32 v94, v96
	v_mov_b32_e32 v95, v88
	v_pk_add_f32 v[78:79], v[78:79], v[84:85]
	v_mov_b32_e32 v88, v97
	v_pk_add_f32 v[78:79], v[78:79], v[94:95]
	v_add_f32_e32 v1, 1.0, v1
	v_pk_add_f32 v[78:79], v[78:79], v[88:89]
	v_rcp_f32_e32 v96, v1
	v_pk_fma_f32 v[78:79], v[78:79], s[80:81], v[86:87] op_sel_hi:[1,0,0]
	v_add_f32_e32 v2, 1.0, v2
	v_mul_f32_e32 v1, 0x4b800000, v79
	v_cmp_gt_f32_e32 vcc, s42, v79
	v_add_f32_e32 v61, 1.0, v61
	v_rcp_f32_e32 v97, v2
	v_cndmask_b32_e32 v1, v79, v1, vcc
	v_rsq_f32_e32 v1, v1
	v_rcp_f32_e32 v100, v61
	v_rcp_f32_e32 v101, v101
	v_pk_mul_f32 v[68:69], v[96:97], v[68:69]
	v_mul_f32_e32 v2, 0x45800000, v1
	v_cndmask_b32_e32 v2, v1, v2, vcc
	v_pk_mul_f32 v[56:57], v[56:57], v[2:3] op_sel_hi:[1,0]
	v_pk_mul_f32 v[58:59], v[58:59], v[2:3] op_sel_hi:[1,0]
	v_pk_mul_f32 v[70:71], v[100:101], v[70:71]
	v_lshlrev_b32_e32 v2, 16, v62
	v_mov_b32_e32 v61, v3
	v_and_b32_e32 v3, 0xffff0000, v62
	v_mul_f32_e32 v1, 0xbfb8aa3b, v2
	v_exp_f32_e32 v1, v1
	v_lshlrev_b32_e32 v62, 16, v63
	v_and_b32_e32 v63, 0xffff0000, v63
	v_cmp_gt_f32_e32 vcc, s42, v78
	v_add_f32_e32 v1, 1.0, v1
	v_lshlrev_b64 v[60:61], 11, v[60:61]
	v_lshl_add_u64 v[60:61], s[16:17], 0, v[60:61]
	v_lshl_add_u64 v[60:61], v[60:61], 0, s[62:63]
	v_lshl_add_u64 v[60:61], v[60:61], 0, v[80:81]
	v_lshl_add_u64 v[60:61], v[60:61], 0, v[74:75]
	s_nop 0
	v_pk_mul_f32 v[56:57], v[240:241], v[56:57]
	v_pk_mul_f32 v[58:59], v[242:243], v[58:59]
	v_pk_mul_f32 v[56:57], v[68:69], v[56:57]
	v_pk_mul_f32 v[58:59], v[70:71], v[58:59]
	v_cvt_pk_bf16_f32 v56, v56, v57
	v_cvt_pk_bf16_f32 v57, v58, v59
	global_store_dwordx2 v[72:73], v[56:57], off offset:1024
	s_nop 0
	v_mul_f32_e32 v64, 0xbfb8aa3b, v3
	v_exp_f32_e32 v64, v64
	v_mul_f32_e32 v65, 0xbfb8aa3b, v62
	v_exp_f32_e32 v65, v65
	v_mul_f32_e32 v66, 0xbfb8aa3b, v63
	v_exp_f32_e32 v66, v66
	v_add_f32_e32 v67, 1.0, v64
	v_rcp_f32_e32 v64, v1
	v_mul_f32_e32 v1, 0x4b800000, v78
	v_cndmask_b32_e32 v1, v78, v1, vcc
	v_add_f32_e32 v68, 1.0, v65
	v_rcp_f32_e32 v65, v67
	v_rsq_f32_e32 v1, v1
	v_add_f32_e32 v69, 1.0, v66
	v_rcp_f32_e32 v66, v68
	v_rcp_f32_e32 v67, v69
	v_pk_mul_f32 v[2:3], v[64:65], v[2:3]
	v_mul_f32_e32 v64, 0x45800000, v1
	v_cndmask_b32_e32 v64, v1, v64, vcc
	v_pk_mul_f32 v[52:53], v[52:53], v[64:65] op_sel_hi:[1,0]
	v_pk_mul_f32 v[54:55], v[54:55], v[64:65] op_sel_hi:[1,0]
	v_pk_mul_f32 v[62:63], v[66:67], v[62:63]
	s_nop 0
	v_pk_mul_f32 v[52:53], v[240:241], v[52:53]
	v_pk_mul_f32 v[54:55], v[242:243], v[54:55]
	v_pk_mul_f32 v[2:3], v[2:3], v[52:53]
	v_pk_mul_f32 v[52:53], v[62:63], v[54:55]
	v_cvt_pk_bf16_f32 v2, v2, v3
	v_cvt_pk_bf16_f32 v3, v52, v53
	global_store_dwordx2 v[60:61], v[2:3], off offset:1024
	s_barrier

.LBB0_805:
	s_or_b64 exec, exec, s[6:7]
	s_lshl_b32 s6, s8, 2
	s_add_u32 s6, s38, s6
	s_addc_u32 s7, s39, 0
	v_lshl_add_u64 v[78:79], v[78:79], 2, s[6:7]
	s_waitcnt lgkmcnt(0)
	s_barrier
	global_load_dwordx4 v[240:243], v[78:79], off
	v_ashrrev_i32_e32 v93, 31, v92
	v_lshl_add_u32 v61, v144, 2, s96
	v_lshlrev_b64 v[84:85], 11, v[2:3]
	v_lshl_add_u32 v2, v73, 2, s96
	s_waitcnt vmcnt(4)
	v_lshlrev_b32_e32 v90, 16, v76
	v_and_b32_e32 v91, 0xffff0000, v76
	v_lshlrev_b32_e32 v98, 16, v77
	v_and_b32_e32 v99, 0xffff0000, v77
	ds_read2st64_b32 v[100:101], v61 offset1:1
	ds_read2st64_b32 v[102:103], v61 offset0:2 offset1:3
	ds_read2st64_b32 v[104:105], v61 offset0:4 offset1:5
	ds_read2st64_b32 v[106:107], v61 offset0:6 offset1:7
	v_lshl_add_u64 v[108:109], s[16:17], 0, v[84:85]
	v_lshlrev_b64 v[84:85], 1, v[92:93]
	ds_read2st64_b32 v[92:93], v2 offset1:1
	ds_read2st64_b32 v[110:111], v2 offset0:2 offset1:3
	ds_read2st64_b32 v[112:113], v2 offset0:4 offset1:5
	ds_read2st64_b32 v[114:115], v2 offset0:6 offset1:7
	v_mul_f32_e32 v61, 0xbfb8aa3b, v90
	v_mul_f32_e32 v73, 0xbfb8aa3b, v91
	v_mul_f32_e32 v81, 0xbfb8aa3b, v98
	v_mul_f32_e32 v116, 0xbfb8aa3b, v99
	v_exp_f32_e32 v2, v61
	v_exp_f32_e32 v61, v73
	v_exp_f32_e32 v73, v81
	v_exp_f32_e32 v81, v116
	s_waitcnt lgkmcnt(3)
	v_mov_b32_e32 v116, v92
	v_mov_b32_e32 v117, v100
	v_mov_b32_e32 v100, v93
	v_pk_add_f32 v[116:117], v[116:117], 0 op_sel_hi:[1,0]
	s_waitcnt lgkmcnt(2)
	v_mov_b32_e32 v92, v110
	v_mov_b32_e32 v93, v102
	v_pk_add_f32 v[100:101], v[116:117], v[100:101]
	v_mov_b32_e32 v102, v111
	v_pk_add_f32 v[92:93], v[100:101], v[92:93]
	s_waitcnt lgkmcnt(1)
	v_mov_b32_e32 v110, v112
	v_mov_b32_e32 v111, v104
	v_pk_add_f32 v[92:93], v[92:93], v[102:103]
	v_mov_b32_e32 v104, v113
	v_pk_add_f32 v[92:93], v[92:93], v[110:111]
	s_waitcnt lgkmcnt(0)
	v_mov_b32_e32 v112, v114
	v_mov_b32_e32 v113, v106
	v_pk_add_f32 v[92:93], v[92:93], v[104:105]
	v_mov_b32_e32 v106, v115
	v_pk_add_f32 v[92:93], v[92:93], v[112:113]
	v_mov_b64_e32 v[86:87], s[82:83]
	v_pk_add_f32 v[92:93], v[92:93], v[106:107]
	v_add_f32_e32 v2, 1.0, v2
	v_pk_fma_f32 v[92:93], v[92:93], s[80:81], v[86:87] op_sel_hi:[1,0,0]
	v_rcp_f32_e32 v114, v2
	v_mul_f32_e32 v2, 0x4b800000, v93
	v_cmp_gt_f32_e32 vcc, s42, v93
	v_add_f32_e32 v61, 1.0, v61
	v_add_f32_e32 v73, 1.0, v73
	v_cndmask_b32_e32 v2, v93, v2, vcc
	v_rsq_f32_e32 v2, v2
	v_add_f32_e32 v81, 1.0, v81
	v_rcp_f32_e32 v115, v61
	v_rcp_f32_e32 v118, v73
	v_rcp_f32_e32 v119, v81
	v_mul_f32_e32 v61, 0x45800000, v2
	v_cndmask_b32_e32 v2, v2, v61, vcc
	v_pk_mul_f32 v[68:69], v[68:69], v[2:3] op_sel_hi:[1,0]
	v_pk_mul_f32 v[70:71], v[70:71], v[2:3] op_sel_hi:[1,0]
	v_lshl_add_u64 v[108:109], v[108:109], 0, s[62:63]
	v_pk_mul_f32 v[90:91], v[114:115], v[90:91]
	v_pk_mul_f32 v[98:99], v[118:119], v[98:99]
	v_lshlrev_b32_e32 v76, 1, v145
	v_mov_b32_e32 v77, v0
	v_lshl_add_u64 v[108:109], v[108:109], 0, v[84:85]
	v_lshl_add_u64 v[100:101], v[108:109], 0, v[76:77]
	v_cmp_gt_f32_e32 vcc, s42, v92
	v_mov_b32_e32 v81, v3
	v_lshlrev_b64 v[80:81], 11, v[80:81]
	v_lshl_add_u64 v[80:81], s[16:17], 0, v[80:81]
	v_lshl_add_u64 v[80:81], v[80:81], 0, s[62:63]
	v_lshl_add_u64 v[80:81], v[80:81], 0, v[84:85]
	v_lshl_add_u64 v[80:81], v[80:81], 0, v[76:77]
	s_cmpk_gt_i32 s50, 0x7ff
	s_mov_b64 s[6:7], -1
	s_waitcnt vmcnt(0)
	v_pk_mul_f32 v[68:69], v[240:241], v[68:69]
	v_pk_mul_f32 v[70:71], v[242:243], v[70:71]
	v_pk_mul_f32 v[68:69], v[90:91], v[68:69]
	v_pk_mul_f32 v[70:71], v[98:99], v[70:71]
	v_cvt_pk_bf16_f32 v68, v68, v69
	v_cvt_pk_bf16_f32 v69, v70, v71
	global_store_dwordx2 v[100:101], v[68:69], off offset:1024
	s_nop 0
	v_lshlrev_b32_e32 v90, 16, v82
	v_mul_f32_e32 v2, 0xbfb8aa3b, v90
	v_exp_f32_e32 v2, v2
	v_and_b32_e32 v91, 0xffff0000, v82
	v_lshlrev_b32_e32 v82, 16, v83
	v_and_b32_e32 v83, 0xffff0000, v83
	v_mul_f32_e32 v61, 0xbfb8aa3b, v91
	v_mul_f32_e32 v73, 0xbfb8aa3b, v82
	v_mul_f32_e32 v93, 0xbfb8aa3b, v83
	v_add_f32_e32 v2, 1.0, v2
	v_exp_f32_e32 v61, v61
	v_exp_f32_e32 v73, v73
	v_exp_f32_e32 v93, v93
	v_rcp_f32_e32 v94, v2
	v_mul_f32_e32 v2, 0x4b800000, v92
	v_cndmask_b32_e32 v2, v92, v2, vcc
	v_rsq_f32_e32 v2, v2
	v_add_f32_e32 v61, 1.0, v61
	v_add_f32_e32 v73, 1.0, v73
	v_add_f32_e32 v93, 1.0, v93
	v_rcp_f32_e32 v95, v61
	v_rcp_f32_e32 v96, v73
	v_rcp_f32_e32 v97, v93
	v_mul_f32_e32 v61, 0x45800000, v2
	v_cndmask_b32_e32 v2, v2, v61, vcc
	v_pk_mul_f32 v[64:65], v[64:65], v[2:3] op_sel_hi:[1,0]
	v_pk_mul_f32 v[66:67], v[66:67], v[2:3] op_sel_hi:[1,0]
	v_pk_mul_f32 v[90:91], v[94:95], v[90:91]
	v_pk_mul_f32 v[82:83], v[96:97], v[82:83]
	v_lshl_add_u32 v2, v89, 2, s96
	v_lshl_add_u32 v61, v88, 2, s96
	v_mov_b32_e32 v73, v3
	v_lshlrev_b64 v[72:73], 11, v[72:73]
	v_lshl_add_u64 v[72:73], s[16:17], 0, v[72:73]
	v_lshl_add_u64 v[72:73], v[72:73], 0, s[62:63]
	v_lshl_add_u64 v[72:73], v[72:73], 0, v[84:85]
	v_lshl_add_u64 v[72:73], v[72:73], 0, v[76:77]
	s_nop 0
	v_pk_mul_f32 v[64:65], v[240:241], v[64:65]
	v_pk_mul_f32 v[66:67], v[242:243], v[66:67]
	v_pk_mul_f32 v[64:65], v[90:91], v[64:65]
	v_pk_mul_f32 v[66:67], v[82:83], v[66:67]
	v_cvt_pk_bf16_f32 v64, v64, v65
	v_cvt_pk_bf16_f32 v65, v66, v67
	global_store_dwordx2 v[80:81], v[64:65], off offset:1024
	s_nop 0
	v_and_b32_e32 v69, 0xffff0000, v74
	v_lshlrev_b32_e32 v70, 16, v75
	v_and_b32_e32 v71, 0xffff0000, v75
	v_mul_f32_e32 v98, 0xbfb8aa3b, v69
	v_mul_f32_e32 v99, 0xbfb8aa3b, v70
	v_mul_f32_e32 v100, 0xbfb8aa3b, v71
	v_lshlrev_b32_e32 v68, 16, v74
	ds_read2st64_b32 v[74:75], v2 offset1:1
	ds_read2st64_b32 v[80:81], v2 offset0:2 offset1:3
	ds_read2st64_b32 v[82:83], v2 offset0:4 offset1:5
	ds_read2st64_b32 v[88:89], v2 offset0:6 offset1:7
	ds_read2st64_b32 v[90:91], v61 offset1:1
	ds_read2st64_b32 v[92:93], v61 offset0:2 offset1:3
	ds_read2st64_b32 v[94:95], v61 offset0:4 offset1:5
	ds_read2st64_b32 v[96:97], v61 offset0:6 offset1:7
	v_exp_f32_e32 v61, v98
	v_exp_f32_e32 v98, v99
	v_exp_f32_e32 v99, v100
	v_mul_f32_e32 v2, 0xbfb8aa3b, v68
	v_exp_f32_e32 v2, v2
	v_add_f32_e32 v100, 1.0, v98
	v_add_f32_e32 v101, 1.0, v99
	s_waitcnt lgkmcnt(3)
	v_mov_b32_e32 v98, v90
	v_mov_b32_e32 v99, v74
	v_mov_b32_e32 v74, v91
	v_pk_add_f32 v[98:99], v[98:99], 0 op_sel_hi:[1,0]
	s_waitcnt lgkmcnt(2)
	v_mov_b32_e32 v90, v92
	v_mov_b32_e32 v91, v80
	v_pk_add_f32 v[74:75], v[98:99], v[74:75]
	v_mov_b32_e32 v80, v93
	v_pk_add_f32 v[74:75], v[74:75], v[90:91]
	s_waitcnt lgkmcnt(1)
	v_mov_b32_e32 v92, v94
	v_mov_b32_e32 v93, v82
	v_pk_add_f32 v[74:75], v[74:75], v[80:81]
	v_mov_b32_e32 v82, v95
	v_pk_add_f32 v[74:75], v[74:75], v[92:93]
	s_waitcnt lgkmcnt(0)
	v_mov_b32_e32 v94, v96
	v_mov_b32_e32 v95, v88
	v_pk_add_f32 v[74:75], v[74:75], v[82:83]
	v_mov_b32_e32 v88, v97
	v_pk_add_f32 v[74:75], v[74:75], v[94:95]
	v_add_f32_e32 v2, 1.0, v2
	v_pk_add_f32 v[74:75], v[74:75], v[88:89]
	v_rcp_f32_e32 v96, v2
	v_pk_fma_f32 v[74:75], v[74:75], s[80:81], v[86:87] op_sel_hi:[1,0,0]
	v_add_f32_e32 v61, 1.0, v61
	v_mul_f32_e32 v2, 0x4b800000, v75
	v_cmp_gt_f32_e32 vcc, s42, v75
	v_rcp_f32_e32 v97, v61
	v_rcp_f32_e32 v100, v100
	v_cndmask_b32_e32 v2, v75, v2, vcc
	v_rsq_f32_e32 v2, v2
	v_rcp_f32_e32 v101, v101
	v_pk_mul_f32 v[68:69], v[96:97], v[68:69]
	v_mul_f32_e32 v61, 0x45800000, v2
	v_cndmask_b32_e32 v2, v2, v61, vcc
	v_pk_mul_f32 v[56:57], v[56:57], v[2:3] op_sel_hi:[1,0]
	v_pk_mul_f32 v[58:59], v[58:59], v[2:3] op_sel_hi:[1,0]
	v_pk_mul_f32 v[70:71], v[100:101], v[70:71]
	v_mov_b32_e32 v61, v3
	v_lshlrev_b32_e32 v2, 16, v62
	v_and_b32_e32 v3, 0xffff0000, v62
	v_lshlrev_b32_e32 v62, 16, v63
	v_and_b32_e32 v63, 0xffff0000, v63
	v_cmp_gt_f32_e32 vcc, s42, v74
	v_lshlrev_b64 v[60:61], 11, v[60:61]
	v_lshl_add_u64 v[60:61], s[16:17], 0, v[60:61]
	v_lshl_add_u64 v[60:61], v[60:61], 0, s[62:63]
	v_lshl_add_u64 v[60:61], v[60:61], 0, v[84:85]
	v_lshl_add_u64 v[60:61], v[60:61], 0, v[76:77]
	s_nop 0
	v_pk_mul_f32 v[56:57], v[240:241], v[56:57]
	v_pk_mul_f32 v[58:59], v[242:243], v[58:59]
	v_pk_mul_f32 v[56:57], v[68:69], v[56:57]
	v_pk_mul_f32 v[58:59], v[70:71], v[58:59]
	v_cvt_pk_bf16_f32 v56, v56, v57
	v_cvt_pk_bf16_f32 v57, v58, v59
	global_store_dwordx2 v[72:73], v[56:57], off offset:1024
	s_nop 0
	v_mul_f32_e32 v64, 0xbfb8aa3b, v2
	v_mul_f32_e32 v65, 0xbfb8aa3b, v3
	v_exp_f32_e32 v64, v64
	v_exp_f32_e32 v65, v65
	v_mul_f32_e32 v66, 0xbfb8aa3b, v62
	v_mul_f32_e32 v67, 0xbfb8aa3b, v63
	v_exp_f32_e32 v66, v66
	v_exp_f32_e32 v67, v67
	v_mul_f32_e32 v68, 0x4b800000, v74
	v_add_f32_e32 v64, 1.0, v64
	v_add_f32_e32 v65, 1.0, v65
	v_cndmask_b32_e32 v68, v74, v68, vcc
	v_rcp_f32_e32 v64, v64
	v_rcp_f32_e32 v65, v65
	v_rsq_f32_e32 v68, v68
	v_add_f32_e32 v66, 1.0, v66
	v_add_f32_e32 v67, 1.0, v67
	v_rcp_f32_e32 v66, v66
	v_rcp_f32_e32 v67, v67
	v_pk_mul_f32 v[2:3], v[64:65], v[2:3]
	v_mul_f32_e32 v64, 0x45800000, v68
	v_cndmask_b32_e32 v64, v68, v64, vcc
	v_pk_mul_f32 v[52:53], v[52:53], v[64:65] op_sel_hi:[1,0]
	v_pk_mul_f32 v[54:55], v[54:55], v[64:65] op_sel_hi:[1,0]
	v_pk_mul_f32 v[62:63], v[66:67], v[62:63]
	s_nop 0
	v_pk_mul_f32 v[52:53], v[240:241], v[52:53]
	v_pk_mul_f32 v[54:55], v[242:243], v[54:55]
	v_pk_mul_f32 v[2:3], v[2:3], v[52:53]
	v_pk_mul_f32 v[52:53], v[62:63], v[54:55]
	v_cvt_pk_bf16_f32 v2, v2, v3
	v_cvt_pk_bf16_f32 v3, v52, v53
	global_store_dwordx2 v[60:61], v[2:3], off offset:1024
	s_barrier
	s_cbranch_scc1 .LBB0_784
	s_add_i32 s2, s89, s2
	s_cmpk_gt_i32 s2, 0x7ff
	s_cbranch_scc1 .LBB0_808
	v_mov_b32_e32 v12, v204
	s_ashr_i32 s6, s2, 8
	v_ashrrev_i32_e32 v2, 31, v12
	v_lshrrev_b32_e32 v2, 28, v2
	v_add_u32_e32 v3, v12, v2
	s_ashr_i32 s7, s6, 31
	s_add_i32 s2, s88, s73
	v_ashrrev_i32_e32 v2, 4, v3
	v_and_b32_e32 v3, 0x1ffffff0, v3
	s_lshl_b64 s[6:7], s[6:7], 12
	s_and_b32 s2, s2, 0xfc0
	v_sub_u32_e32 v3, v12, v3
	s_or_b32 s6, s6, s2
	v_lshlrev_b32_e32 v4, 3, v3
	v_ashrrev_i32_e32 v3, 31, v2
	s_add_i32 s2, s91, s61
	v_lshl_add_u64 v[2:3], s[6:7], 0, v[2:3]
	v_mov_b64_e32 v[6:7], s[66:67]
	s_and_b32 s2, s2, 0x180
	v_mad_u64_u32 v[8:9], s[8:9], v2, s0, v[6:7]
	v_mad_i32_i24 v9, v3, s0, v9
	s_lshl_b32 s62, s2, 1
	v_lshl_add_u64 v[2:3], v[8:9], 0, s[62:63]
	v_ashrrev_i32_e32 v5, 31, v4
	v_lshl_add_u64 v[2:3], v[4:5], 1, v[2:3]
	v_add_u32_e32 v5, 0x200, v12
	v_ashrrev_i32_e32 v4, 31, v5
	v_lshrrev_b32_e32 v4, 28, v4
	v_add_u32_e32 v8, v5, v4
	v_ashrrev_i32_e32 v4, 4, v8
	v_and_b32_e32 v8, 0x1ffffff0, v8
	v_sub_u32_e32 v5, v5, v8
	v_lshlrev_b32_e32 v8, 3, v5
	v_ashrrev_i32_e32 v5, 31, v4
	v_lshl_add_u64 v[4:5], s[6:7], 0, v[4:5]
	v_mad_u64_u32 v[6:7], s[8:9], v4, s0, v[6:7]
	v_mad_i32_i24 v7, v5, s0, v7
	v_add_co_u32_e32 v2, vcc, s48, v2
	v_lshl_add_u64 v[4:5], v[6:7], 0, s[62:63]
	v_ashrrev_i32_e32 v9, 31, v8
	v_addc_co_u32_e32 v3, vcc, 0, v3, vcc
	v_lshl_add_u64 v[4:5], v[8:9], 1, v[4:5]
	v_add_co_u32_e32 v8, vcc, s48, v4
	s_add_u32 s8, s66, s62
	s_nop 0
	v_addc_co_u32_e32 v9, vcc, 0, v5, vcc
	global_load_dwordx4 v[4:7], v[2:3], off offset:1024
	s_nop 0
	global_load_dwordx4 v[8:11], v[8:9], off offset:1024
	v_ashrrev_i32_e32 v2, 4, v12
	v_lshlrev_b32_e32 v3, 4, v12
	s_addc_u32 s9, s67, 0
	v_and_b32_e32 v12, 0xf0, v3
	v_mov_b32_e32 v13, v0
	v_ashrrev_i32_e32 v3, 31, v2
	v_lshl_add_u64 v[12:13], s[8:9], 0, v[12:13]
	v_lshl_add_u64 v[14:15], s[6:7], 0, v[2:3]
	v_add_u32_e32 v2, 32, v2
	v_mad_u64_u32 v[20:21], s[8:9], v14, s0, v[12:13]
	v_ashrrev_i32_e32 v3, 31, v2
	v_mad_i32_i24 v21, v15, s0, v21
	v_add_co_u32_e32 v28, vcc, s48, v20
	v_lshl_add_u64 v[2:3], s[6:7], 0, v[2:3]
	s_nop 0
	v_addc_co_u32_e32 v29, vcc, 0, v21, vcc
	v_mad_u64_u32 v[30:31], s[6:7], v2, s0, v[12:13]
	v_mad_i32_i24 v31, v3, s0, v31
	v_add_co_u32_e32 v2, vcc, 0x1000, v30
	global_load_dwordx4 v[12:15], v[20:21], off offset:3072
	s_nop 0
	global_load_dwordx4 v[20:23], v[30:31], off offset:3072
	v_addc_co_u32_e32 v3, vcc, 0, v31, vcc
	global_load_dwordx4 v[28:31], v[28:29], off
	s_nop 0
	global_load_dwordx4 v[32:35], v[2:3], off

.LBB0_899:
	s_ashr_i32 s31, s30, 31
	v_cmp_lt_i64_e32 vcc, s[36:37], v[188:189]
	s_lshl_b64 s[36:37], s[30:31], 19
	s_add_u32 s36, s12, s36
	s_addc_u32 s37, s13, s37
	s_and_b64 s[38:39], vcc, exec
	s_cselect_b32 s31, s37, s55
	s_cselect_b32 s51, s36, s54
	s_ashr_i32 s27, s26, 31
	s_lshl_b64 s[38:39], s[26:27], 19
	s_add_u32 s38, s1, s38
	s_addc_u32 s39, s2, s39
	s_and_b64 s[58:59], vcc, exec
	s_cselect_b32 s27, s39, s57
	s_cselect_b32 s53, s38, s56
	s_add_u32 s54, s54, 0x40080
	s_addc_u32 s55, s55, 0
	s_add_u32 s60, s56, 0x100
	v_mov_b32_e32 v0, 0
	s_addc_u32 s61, s57, 0
	s_mov_b32 s62, -2
	s_waitcnt lgkmcnt(0)
	v_mov_b32_e32 v1, v0
	v_mov_b32_e32 v2, v0
	v_mov_b32_e32 v3, v0
	v_mov_b32_e32 v4, v0
	v_mov_b32_e32 v5, v0
	v_mov_b32_e32 v6, v0
	v_mov_b32_e32 v7, v0
	v_mov_b32_e32 v16, v0
	v_mov_b32_e32 v17, v0
	v_mov_b32_e32 v18, v0
	v_mov_b32_e32 v19, v0
	v_mov_b32_e32 v20, v0
	v_mov_b32_e32 v21, v0
	v_mov_b32_e32 v22, v0
	v_mov_b32_e32 v23, v0

	v_mov_b32_e32 v32, v0
	v_mov_b32_e32 v33, v0
	v_mov_b32_e32 v34, v0
	v_mov_b32_e32 v35, v0
	v_mov_b32_e32 v36, v0
	v_mov_b32_e32 v37, v0
	v_mov_b32_e32 v38, v0
	v_mov_b32_e32 v39, v0
	v_mov_b32_e32 v48, v0
	v_mov_b32_e32 v49, v0
	v_mov_b32_e32 v50, v0
	v_mov_b32_e32 v51, v0
	v_mov_b32_e32 v52, v0
	v_mov_b32_e32 v53, v0
	v_mov_b32_e32 v54, v0
	v_mov_b32_e32 v55, v0
	v_mov_b32_e32 v8, v0
	v_mov_b32_e32 v9, v0
	v_mov_b32_e32 v10, v0
	v_mov_b32_e32 v11, v0
	v_mov_b32_e32 v12, v0
	v_mov_b32_e32 v13, v0
	v_mov_b32_e32 v14, v0
	v_mov_b32_e32 v15, v0
	v_mov_b32_e32 v24, v0
	v_mov_b32_e32 v25, v0
	v_mov_b32_e32 v26, v0
	v_mov_b32_e32 v27, v0
	v_mov_b32_e32 v28, v0
	v_mov_b32_e32 v29, v0
	v_mov_b32_e32 v30, v0
	v_mov_b32_e32 v31, v0
	v_mov_b32_e32 v40, v0
	v_mov_b32_e32 v41, v0
	v_mov_b32_e32 v42, v0
	v_mov_b32_e32 v43, v0
	v_mov_b32_e32 v44, v0
	v_mov_b32_e32 v45, v0
	v_mov_b32_e32 v46, v0
	v_mov_b32_e32 v47, v0
	v_mov_b32_e32 v56, v0
	v_mov_b32_e32 v57, v0
	v_mov_b32_e32 v58, v0
	v_mov_b32_e32 v59, v0
	v_mov_b32_e32 v60, v0
	v_mov_b32_e32 v61, v0
	v_mov_b32_e32 v62, v0
	v_mov_b32_e32 v63, v0
	v_mov_b32_e32 v64, v0
	v_mov_b32_e32 v65, v0
	v_mov_b32_e32 v66, v0
	v_mov_b32_e32 v67, v0
	v_mov_b32_e32 v68, v0
	v_mov_b32_e32 v69, v0
	v_mov_b32_e32 v70, v0
	v_mov_b32_e32 v71, v0
	v_mov_b32_e32 v80, v0
	v_mov_b32_e32 v81, v0
	v_mov_b32_e32 v82, v0
	v_mov_b32_e32 v83, v0
	v_mov_b32_e32 v84, v0
	v_mov_b32_e32 v85, v0
	v_mov_b32_e32 v86, v0
	v_mov_b32_e32 v87, v0
	v_mov_b32_e32 v96, v0
	v_mov_b32_e32 v97, v0
	v_mov_b32_e32 v98, v0
	v_mov_b32_e32 v99, v0
	v_mov_b32_e32 v100, v0
	v_mov_b32_e32 v101, v0
	v_mov_b32_e32 v102, v0
	v_mov_b32_e32 v103, v0
	v_mov_b32_e32 v112, v0
	v_mov_b32_e32 v113, v0
	v_mov_b32_e32 v114, v0
	v_mov_b32_e32 v115, v0
	v_mov_b32_e32 v116, v0
	v_mov_b32_e32 v117, v0
	v_mov_b32_e32 v118, v0
	v_mov_b32_e32 v119, v0
	v_mov_b32_e32 v72, v0
	v_mov_b32_e32 v73, v0
	v_mov_b32_e32 v74, v0
	v_mov_b32_e32 v75, v0
	v_mov_b32_e32 v76, v0
	v_mov_b32_e32 v77, v0
	v_mov_b32_e32 v78, v0
	v_mov_b32_e32 v79, v0
	v_mov_b32_e32 v88, v0
	v_mov_b32_e32 v89, v0
	v_mov_b32_e32 v90, v0
	v_mov_b32_e32 v91, v0
	v_mov_b32_e32 v92, v0
	v_mov_b32_e32 v93, v0
	v_mov_b32_e32 v94, v0
	v_mov_b32_e32 v95, v0
	v_mov_b32_e32 v104, v0
	v_mov_b32_e32 v105, v0
	v_mov_b32_e32 v106, v0
	v_mov_b32_e32 v107, v0
	v_mov_b32_e32 v108, v0
	v_mov_b32_e32 v109, v0
	v_mov_b32_e32 v110, v0
	v_mov_b32_e32 v111, v0
	v_mov_b32_e32 v120, v0
	v_mov_b32_e32 v121, v0
	v_mov_b32_e32 v122, v0
	v_mov_b32_e32 v123, v0
	v_mov_b32_e32 v124, v0
	v_mov_b32_e32 v125, v0
	v_mov_b32_e32 v126, v0
	v_mov_b32_e32 v127, v0

.LBB0_1061:
	s_ashr_i32 s27, s26, 31
	v_cmp_lt_i64_e32 vcc, s[28:29], v[164:165]
	s_lshl_b64 s[28:29], s[26:27], 21
	s_add_u32 s28, s1, s28
	s_addc_u32 s29, s2, s29
	s_and_b64 s[30:31], vcc, exec
	s_cselect_b32 s27, s29, s51
	s_cselect_b32 s37, s28, s50
	s_ashr_i32 s25, s24, 31
	s_lshl_b64 s[30:31], s[24:25], 21
	s_add_u32 s30, s20, s30
	s_addc_u32 s31, s21, s31
	s_and_b64 s[54:55], vcc, exec
	s_cselect_b32 s25, s31, s53
	s_cselect_b32 s57, s30, s52
	s_add_u32 s50, s50, 0x100080
	s_addc_u32 s51, s51, 0
	s_add_u32 s58, s52, 0x100
	v_mov_b32_e32 v0, 0
	s_addc_u32 s59, s53, 0
	s_mov_b32 s60, -2
	s_waitcnt lgkmcnt(0)
	v_mov_b32_e32 v1, v0
	v_mov_b32_e32 v2, v0
	v_mov_b32_e32 v3, v0
	v_mov_b32_e32 v4, v0
	v_mov_b32_e32 v5, v0
	v_mov_b32_e32 v6, v0
	v_mov_b32_e32 v7, v0
	v_mov_b32_e32 v16, v0
	v_mov_b32_e32 v17, v0
	v_mov_b32_e32 v18, v0
	v_mov_b32_e32 v19, v0
	v_mov_b32_e32 v20, v0
	v_mov_b32_e32 v21, v0
	v_mov_b32_e32 v22, v0
	v_mov_b32_e32 v23, v0

	v_mov_b32_e32 v32, v0
	v_mov_b32_e32 v33, v0
	v_mov_b32_e32 v34, v0
	v_mov_b32_e32 v35, v0
	v_mov_b32_e32 v36, v0
	v_mov_b32_e32 v37, v0
	v_mov_b32_e32 v38, v0
	v_mov_b32_e32 v39, v0
	v_mov_b32_e32 v48, v0
	v_mov_b32_e32 v49, v0
	v_mov_b32_e32 v50, v0
	v_mov_b32_e32 v51, v0
	v_mov_b32_e32 v52, v0
	v_mov_b32_e32 v53, v0
	v_mov_b32_e32 v54, v0
	v_mov_b32_e32 v55, v0
	v_mov_b32_e32 v8, v0
	v_mov_b32_e32 v9, v0
	v_mov_b32_e32 v10, v0
	v_mov_b32_e32 v11, v0
	v_mov_b32_e32 v12, v0
	v_mov_b32_e32 v13, v0
	v_mov_b32_e32 v14, v0
	v_mov_b32_e32 v15, v0
	v_mov_b32_e32 v24, v0
	v_mov_b32_e32 v25, v0
	v_mov_b32_e32 v26, v0
	v_mov_b32_e32 v27, v0
	v_mov_b32_e32 v28, v0
	v_mov_b32_e32 v29, v0
	v_mov_b32_e32 v30, v0
	v_mov_b32_e32 v31, v0
	v_mov_b32_e32 v40, v0
	v_mov_b32_e32 v41, v0
	v_mov_b32_e32 v42, v0
	v_mov_b32_e32 v43, v0
	v_mov_b32_e32 v44, v0
	v_mov_b32_e32 v45, v0
	v_mov_b32_e32 v46, v0
	v_mov_b32_e32 v47, v0
	v_mov_b32_e32 v56, v0
	v_mov_b32_e32 v57, v0
	v_mov_b32_e32 v58, v0
	v_mov_b32_e32 v59, v0
	v_mov_b32_e32 v60, v0
	v_mov_b32_e32 v61, v0
	v_mov_b32_e32 v62, v0
	v_mov_b32_e32 v63, v0
	v_mov_b32_e32 v64, v0
	v_mov_b32_e32 v65, v0
	v_mov_b32_e32 v66, v0
	v_mov_b32_e32 v67, v0
	v_mov_b32_e32 v68, v0
	v_mov_b32_e32 v69, v0
	v_mov_b32_e32 v70, v0
	v_mov_b32_e32 v71, v0
	v_mov_b32_e32 v80, v0
	v_mov_b32_e32 v81, v0
	v_mov_b32_e32 v82, v0
	v_mov_b32_e32 v83, v0
	v_mov_b32_e32 v84, v0
	v_mov_b32_e32 v85, v0
	v_mov_b32_e32 v86, v0
	v_mov_b32_e32 v87, v0
	v_mov_b32_e32 v96, v0
	v_mov_b32_e32 v97, v0
	v_mov_b32_e32 v98, v0
	v_mov_b32_e32 v99, v0
	v_mov_b32_e32 v100, v0
	v_mov_b32_e32 v101, v0
	v_mov_b32_e32 v102, v0
	v_mov_b32_e32 v103, v0
	v_mov_b32_e32 v112, v0
	v_mov_b32_e32 v113, v0
	v_mov_b32_e32 v114, v0
	v_mov_b32_e32 v115, v0
	v_mov_b32_e32 v116, v0
	v_mov_b32_e32 v117, v0
	v_mov_b32_e32 v118, v0
	v_mov_b32_e32 v119, v0
	v_mov_b32_e32 v72, v0
	v_mov_b32_e32 v73, v0
	v_mov_b32_e32 v74, v0
	v_mov_b32_e32 v75, v0
	v_mov_b32_e32 v76, v0
	v_mov_b32_e32 v77, v0
	v_mov_b32_e32 v78, v0
	v_mov_b32_e32 v79, v0
	v_mov_b32_e32 v88, v0
	v_mov_b32_e32 v89, v0
	v_mov_b32_e32 v90, v0
	v_mov_b32_e32 v91, v0
	v_mov_b32_e32 v92, v0
	v_mov_b32_e32 v93, v0
	v_mov_b32_e32 v94, v0
	v_mov_b32_e32 v95, v0
	v_mov_b32_e32 v104, v0
	v_mov_b32_e32 v105, v0
	v_mov_b32_e32 v106, v0
	v_mov_b32_e32 v107, v0
	v_mov_b32_e32 v108, v0
	v_mov_b32_e32 v109, v0
	v_mov_b32_e32 v110, v0
	v_mov_b32_e32 v111, v0
	v_mov_b32_e32 v120, v0
	v_mov_b32_e32 v121, v0
	v_mov_b32_e32 v122, v0
	v_mov_b32_e32 v123, v0
	v_mov_b32_e32 v124, v0
	v_mov_b32_e32 v125, v0
	v_mov_b32_e32 v126, v0
	v_mov_b32_e32 v127, v0

.LBB0_1594:
	s_or_b64 exec, exec, s[12:13]
	s_add_i32 s82, s81, s61
	s_lshl_b32 s12, s2, 2
	s_add_u32 s12, s26, s12
	s_addc_u32 s13, s27, 0
	v_lshl_add_u32 v0, v131, 2, s96
	v_lshl_add_u64 v[84:85], v[84:85], 2, s[12:13]
	s_waitcnt lgkmcnt(0)
	s_barrier
	ds_read2st64_b32 v[94:95], v0 offset1:1
	ds_read2st64_b32 v[96:97], v0 offset0:2 offset1:3
	ds_read2st64_b32 v[98:99], v0 offset0:4 offset1:5
	ds_read2st64_b32 v[100:101], v0 offset0:6 offset1:7
	global_load_dwordx4 v[244:247], v[84:85], off offset:16
	global_load_dwordx4 v[240:243], v[84:85], off
	s_waitcnt vmcnt(5)
	v_lshlrev_b32_e32 v104, 16, v72
	v_and_b32_e32 v105, 0xffff0000, v72
	v_mul_f32_e32 v0, 0xbfb8aa3b, v104
	v_lshlrev_b64 v[102:103], 11, v[2:3]
	v_exp_f32_e32 v0, v0
	v_mul_f32_e32 v2, 0xbfb8aa3b, v105
	v_exp_f32_e32 v2, v2
	v_lshlrev_b32_e32 v106, 16, v73
	v_add_f32_e32 v0, 1.0, v0
	v_rcp_f32_e32 v72, v0
	v_add_f32_e32 v0, 1.0, v2
	v_mul_f32_e32 v2, 0xbfb8aa3b, v106
	v_exp_f32_e32 v2, v2
	v_and_b32_e32 v107, 0xffff0000, v73
	v_mul_f32_e32 v73, 0xbfb8aa3b, v107
	v_lshlrev_b32_e32 v110, 16, v74
	v_exp_f32_e32 v109, v73
	v_rcp_f32_e32 v73, v0
	v_add_f32_e32 v0, 1.0, v2
	v_and_b32_e32 v111, 0xffff0000, v74
	v_mul_f32_e32 v2, 0xbfb8aa3b, v110
	v_exp_f32_e32 v2, v2
	v_mul_f32_e32 v74, 0xbfb8aa3b, v111
	v_exp_f32_e32 v112, v74
	v_rcp_f32_e32 v108, v0
	v_add_f32_e32 v0, 1.0, v109
	v_rcp_f32_e32 v109, v0
	v_add_f32_e32 v0, 1.0, v2
	v_rcp_f32_e32 v74, v0
	v_add_f32_e32 v0, 1.0, v112
	v_lshlrev_b32_e32 v112, 16, v75
	v_and_b32_e32 v113, 0xffff0000, v75
	v_mul_f32_e32 v2, 0xbfb8aa3b, v112
	v_exp_f32_e32 v2, v2
	v_mul_f32_e32 v75, 0xbfb8aa3b, v113
	v_exp_f32_e32 v115, v75
	v_rcp_f32_e32 v75, v0
	v_add_f32_e32 v0, 1.0, v2
	v_rcp_f32_e32 v114, v0
	v_add_f32_e32 v0, 1.0, v115
	v_rcp_f32_e32 v115, v0
	v_lshl_add_u32 v0, v129, 2, s96
	v_pk_mul_f32 v[106:107], v[108:109], v[106:107]
	v_pk_mul_f32 v[108:109], v[74:75], v[110:111]
	ds_read2st64_b32 v[74:75], v0 offset1:1
	v_pk_mul_f32 v[110:111], v[114:115], v[112:113]
	ds_read2st64_b32 v[112:113], v0 offset0:2 offset1:3
	ds_read2st64_b32 v[114:115], v0 offset0:4 offset1:5
	ds_read2st64_b32 v[116:117], v0 offset0:6 offset1:7
	s_waitcnt lgkmcnt(7)
	v_mov_b32_e32 v119, v94
	v_ashrrev_i32_e32 v133, 31, v132
	s_waitcnt lgkmcnt(3)
	v_mov_b32_e32 v118, v74
	v_pk_add_f32 v[118:119], v[118:119], 0 op_sel_hi:[1,0]
	v_mov_b32_e32 v94, v75
	v_pk_add_f32 v[74:75], v[118:119], v[94:95]
	s_waitcnt lgkmcnt(2)
	v_mov_b32_e32 v94, v112
	v_mov_b32_e32 v95, v96
	v_pk_add_f32 v[74:75], v[74:75], v[94:95]
	v_mov_b32_e32 v96, v113
	v_pk_add_f32 v[74:75], v[74:75], v[96:97]
	s_waitcnt lgkmcnt(1)
	v_mov_b32_e32 v94, v114
	v_mov_b32_e32 v95, v98
	v_pk_add_f32 v[74:75], v[74:75], v[94:95]
	v_mov_b32_e32 v98, v115
	v_pk_add_f32 v[74:75], v[74:75], v[98:99]
	s_waitcnt lgkmcnt(0)
	v_mov_b32_e32 v94, v116
	v_mov_b32_e32 v95, v100
	v_pk_add_f32 v[74:75], v[74:75], v[94:95]
	v_mov_b32_e32 v100, v117
	v_pk_add_f32 v[94:95], v[74:75], v[100:101]
	v_mov_b64_e32 v[74:75], s[60:61]
	v_pk_fma_f32 v[94:95], v[94:95], s[58:59], v[74:75] op_sel_hi:[1,0,0]
	v_lshl_add_u64 v[102:103], s[28:29], 0, v[102:103]
	v_mul_f32_e32 v0, 0x4b800000, v95
	v_cmp_gt_f32_e32 vcc, s59, v95
	s_lshl_b32 s38, s2, 1
	v_pk_mul_f32 v[104:105], v[72:73], v[104:105]
	v_cndmask_b32_e32 v0, v95, v0, vcc
	v_rsq_f32_e32 v0, v0
	v_lshl_add_u64 v[102:103], v[102:103], 0, s[38:39]
	v_lshlrev_b64 v[72:73], 1, v[132:133]
	v_lshl_add_u64 v[96:97], v[102:103], 0, v[72:73]
	v_mul_f32_e32 v2, 0x45800000, v0
	v_cndmask_b32_e32 v0, v0, v2, vcc
	v_pk_mul_f32 v[80:81], v[80:81], v[0:1] op_sel_hi:[1,0]
	v_pk_mul_f32 v[82:83], v[82:83], v[0:1] op_sel_hi:[1,0]
	v_pk_mul_f32 v[76:77], v[76:77], v[0:1] op_sel_hi:[1,0]
	v_pk_mul_f32 v[78:79], v[78:79], v[0:1] op_sel_hi:[1,0]
	s_waitcnt vmcnt(0)
	v_pk_mul_f32 v[80:81], v[240:241], v[80:81]
	v_pk_mul_f32 v[82:83], v[242:243], v[82:83]
	v_pk_mul_f32 v[76:77], v[244:245], v[76:77]
	v_pk_mul_f32 v[78:79], v[246:247], v[78:79]
	v_mov_b32_e32 v127, v1
	v_pk_mul_f32 v[80:81], v[104:105], v[80:81]
	v_pk_mul_f32 v[82:83], v[106:107], v[82:83]
	v_pk_mul_f32 v[76:77], v[108:109], v[76:77]
	v_pk_mul_f32 v[78:79], v[110:111], v[78:79]
	v_lshl_add_u64 v[96:97], v[96:97], 0, v[126:127]
	v_cvt_pk_bf16_f32 v80, v80, v81
	v_cvt_pk_bf16_f32 v81, v82, v83
	v_cvt_pk_bf16_f32 v82, v76, v77
	v_cvt_pk_bf16_f32 v83, v78, v79
	global_store_dwordx4 v[96:97], v[80:83], off
	s_nop 1
	s_nop 0
	s_nop 0
	s_nop 0
	v_lshlrev_b32_e32 v86, 16, v68
	v_and_b32_e32 v87, 0xffff0000, v68
	v_lshlrev_b32_e32 v68, 16, v69
	v_and_b32_e32 v69, 0xffff0000, v69
	v_mul_f32_e32 v0, 0xbfb8aa3b, v86
	v_mul_f32_e32 v92, 0xbfb8aa3b, v69
	v_exp_f32_e32 v0, v0
	v_exp_f32_e32 v92, v92
	v_lshlrev_b32_e32 v88, 16, v70
	v_and_b32_e32 v89, 0xffff0000, v70
	v_mul_f32_e32 v2, 0xbfb8aa3b, v87
	v_mul_f32_e32 v70, 0xbfb8aa3b, v68
	v_add_f32_e32 v0, 1.0, v0
	v_mul_f32_e32 v93, 0xbfb8aa3b, v88
	v_exp_f32_e32 v2, v2
	v_exp_f32_e32 v70, v70
	v_add_f32_e32 v97, 1.0, v92
	v_rcp_f32_e32 v92, v0
	v_mul_f32_e32 v0, 0x4b800000, v94
	v_cmp_gt_f32_e32 vcc, s59, v94
	v_exp_f32_e32 v93, v93
	v_add_f32_e32 v2, 1.0, v2
	v_cndmask_b32_e32 v0, v94, v0, vcc
	v_rsq_f32_e32 v0, v0
	v_add_f32_e32 v70, 1.0, v70
	v_add_f32_e32 v98, 1.0, v93
	v_rcp_f32_e32 v93, v2
	v_rcp_f32_e32 v96, v70
	v_rcp_f32_e32 v97, v97
	v_mul_f32_e32 v2, 0x45800000, v0
	v_cndmask_b32_e32 v0, v0, v2, vcc
	v_pk_mul_f32 v[64:65], v[64:65], v[0:1] op_sel_hi:[1,0]
	v_pk_mul_f32 v[66:67], v[66:67], v[0:1] op_sel_hi:[1,0]
	v_pk_mul_f32 v[86:87], v[92:93], v[86:87]
	v_pk_mul_f32 v[68:69], v[96:97], v[68:69]
	v_pk_mul_f32 v[60:61], v[60:61], v[0:1] op_sel_hi:[1,0]
	v_mul_f32_e32 v95, 0xbfb8aa3b, v89
	v_exp_f32_e32 v95, v95
	v_rcp_f32_e32 v94, v98
	v_mov_b32_e32 v131, v3
	v_pk_mul_f32 v[62:63], v[62:63], v[0:1] op_sel_hi:[1,0]
	v_add_f32_e32 v95, 1.0, v95
	v_rcp_f32_e32 v95, v95
	v_lshlrev_b64 v[90:91], 11, v[130:131]
	v_lshl_add_u64 v[90:91], s[28:29], 0, v[90:91]
	v_lshl_add_u32 v0, v177, 2, s96
	v_mov_b32_e32 v129, v3
	s_add_i32 s80, s80, s75
	s_add_i32 s79, s79, s76
	s_cmpk_gt_i32 s82, 0x3ff
	s_cselect_b64 s[12:13], -1, 0
	s_nop 0
	v_pk_mul_f32 v[64:65], v[240:241], v[64:65]
	v_pk_mul_f32 v[66:67], v[242:243], v[66:67]
	s_nop 0
	v_pk_mul_f32 v[76:77], v[244:245], v[60:61]
	v_pk_mul_f32 v[60:61], v[86:87], v[64:65]
	v_pk_mul_f32 v[64:65], v[68:69], v[66:67]
	v_cvt_pk_bf16_f32 v60, v60, v61
	v_cvt_pk_bf16_f32 v61, v64, v65
	v_lshlrev_b32_e32 v64, 16, v71
	v_and_b32_e32 v65, 0xffff0000, v71
	v_mul_f32_e32 v2, 0xbfb8aa3b, v64
	v_exp_f32_e32 v2, v2
	v_mul_f32_e32 v66, 0xbfb8aa3b, v65
	v_exp_f32_e32 v69, v66
	v_pk_mul_f32 v[62:63], v[246:247], v[62:63]
	v_add_f32_e32 v2, 1.0, v2
	v_rcp_f32_e32 v68, v2
	v_add_f32_e32 v2, 1.0, v69
	v_rcp_f32_e32 v69, v2
	v_pk_mul_f32 v[66:67], v[94:95], v[88:89]
	v_lshlrev_b32_e32 v82, 16, v56
	v_pk_mul_f32 v[66:67], v[66:67], v[76:77]
	v_pk_mul_f32 v[64:65], v[68:69], v[64:65]
	v_and_b32_e32 v83, 0xffff0000, v56
	v_pk_mul_f32 v[64:65], v[64:65], v[62:63]
	v_cvt_pk_bf16_f32 v62, v66, v67
	v_cvt_pk_bf16_f32 v63, v64, v65
	v_lshl_add_u64 v[64:65], v[90:91], 0, s[38:39]
	v_lshl_add_u64 v[64:65], v[64:65], 0, v[72:73]
	v_lshl_add_u64 v[64:65], v[64:65], 0, v[126:127]
	global_store_dwordx4 v[64:65], v[60:63], off
	s_nop 1
	ds_read2st64_b32 v[68:69], v0 offset1:1
	ds_read2st64_b32 v[70:71], v0 offset0:2 offset1:3
	ds_read2st64_b32 v[76:77], v0 offset0:4 offset1:5
	ds_read2st64_b32 v[78:79], v0 offset0:6 offset1:7
	s_nop 0
	s_nop 0
	v_mul_f32_e32 v0, 0xbfb8aa3b, v82
	v_exp_f32_e32 v0, v0
	v_mul_f32_e32 v2, 0xbfb8aa3b, v83
	v_exp_f32_e32 v2, v2
	v_lshlrev_b32_e32 v56, 16, v57
	v_add_f32_e32 v0, 1.0, v0
	v_rcp_f32_e32 v86, v0
	v_add_f32_e32 v0, 1.0, v2
	v_rcp_f32_e32 v87, v0
	v_and_b32_e32 v57, 0xffff0000, v57
	v_mul_f32_e32 v0, 0xbfb8aa3b, v56
	v_exp_f32_e32 v0, v0
	v_mul_f32_e32 v2, 0xbfb8aa3b, v57
	v_exp_f32_e32 v2, v2
	v_pk_mul_f32 v[82:83], v[86:87], v[82:83]
	v_add_f32_e32 v0, 1.0, v0
	v_rcp_f32_e32 v86, v0
	v_add_f32_e32 v0, 1.0, v2
	v_lshlrev_b32_e32 v88, 16, v58
	v_rcp_f32_e32 v87, v0
	v_and_b32_e32 v89, 0xffff0000, v58
	v_mul_f32_e32 v0, 0xbfb8aa3b, v88
	v_exp_f32_e32 v0, v0
	v_mul_f32_e32 v2, 0xbfb8aa3b, v89
	v_exp_f32_e32 v2, v2
	v_pk_mul_f32 v[56:57], v[86:87], v[56:57]
	v_add_f32_e32 v0, 1.0, v0
	v_lshlrev_b32_e32 v86, 16, v59
	v_rcp_f32_e32 v58, v0
	v_add_f32_e32 v0, 1.0, v2
	v_and_b32_e32 v87, 0xffff0000, v59
	v_mul_f32_e32 v2, 0xbfb8aa3b, v86
	v_exp_f32_e32 v2, v2
	v_mul_f32_e32 v59, 0xbfb8aa3b, v87
	v_exp_f32_e32 v91, v59
	v_rcp_f32_e32 v59, v0
	v_add_f32_e32 v0, 1.0, v2
	v_rcp_f32_e32 v90, v0
	v_add_f32_e32 v0, 1.0, v91
	v_rcp_f32_e32 v91, v0
	v_lshl_add_u32 v0, v125, 2, s96
	v_pk_mul_f32 v[58:59], v[58:59], v[88:89]
	ds_read2st64_b32 v[88:89], v0 offset1:1
	v_pk_mul_f32 v[86:87], v[90:91], v[86:87]
	ds_read2st64_b32 v[90:91], v0 offset0:2 offset1:3
	ds_read2st64_b32 v[92:93], v0 offset0:4 offset1:5
	ds_read2st64_b32 v[94:95], v0 offset0:6 offset1:7
	s_waitcnt lgkmcnt(7)
	v_mov_b32_e32 v97, v68
	v_lshlrev_b64 v[80:81], 11, v[128:129]
	s_waitcnt lgkmcnt(3)
	v_mov_b32_e32 v96, v88
	v_pk_add_f32 v[96:97], v[96:97], 0 op_sel_hi:[1,0]
	v_mov_b32_e32 v68, v89
	v_pk_add_f32 v[68:69], v[96:97], v[68:69]
	s_waitcnt lgkmcnt(2)
	v_mov_b32_e32 v88, v90
	v_mov_b32_e32 v89, v70
	v_pk_add_f32 v[68:69], v[68:69], v[88:89]
	v_mov_b32_e32 v70, v91
	v_pk_add_f32 v[68:69], v[68:69], v[70:71]
	s_waitcnt lgkmcnt(1)
	v_mov_b32_e32 v70, v92
	v_mov_b32_e32 v71, v76
	v_pk_add_f32 v[68:69], v[68:69], v[70:71]
	v_mov_b32_e32 v76, v93
	v_pk_add_f32 v[68:69], v[68:69], v[76:77]
	s_waitcnt lgkmcnt(0)
	v_mov_b32_e32 v70, v94
	v_mov_b32_e32 v71, v78
	v_pk_add_f32 v[68:69], v[68:69], v[70:71]
	v_mov_b32_e32 v78, v95
	v_pk_add_f32 v[68:69], v[68:69], v[78:79]
	v_lshl_add_u64 v[80:81], s[28:29], 0, v[80:81]
	v_pk_fma_f32 v[68:69], v[68:69], s[58:59], v[74:75] op_sel_hi:[1,0,0]
	v_lshl_add_u64 v[70:71], v[80:81], 0, s[38:39]
	v_mul_f32_e32 v0, 0x4b800000, v69
	v_cmp_gt_f32_e32 vcc, s59, v69
	v_lshl_add_u64 v[70:71], v[70:71], 0, v[72:73]
	v_lshl_add_u64 v[70:71], v[70:71], 0, v[126:127]
	v_cndmask_b32_e32 v0, v69, v0, vcc
	v_rsq_f32_e32 v0, v0
	v_mov_b32_e32 v125, v3
	v_and_b32_e32 v3, 0xffff0000, v44
	v_mul_f32_e32 v2, 0x45800000, v0
	v_cndmask_b32_e32 v0, v0, v2, vcc
	v_pk_mul_f32 v[52:53], v[52:53], v[0:1] op_sel_hi:[1,0]
	v_pk_mul_f32 v[54:55], v[54:55], v[0:1] op_sel_hi:[1,0]
	v_pk_mul_f32 v[48:49], v[48:49], v[0:1] op_sel_hi:[1,0]
	v_pk_mul_f32 v[50:51], v[50:51], v[0:1] op_sel_hi:[1,0]
	s_nop 0
	v_pk_mul_f32 v[52:53], v[240:241], v[52:53]
	v_pk_mul_f32 v[54:55], v[242:243], v[54:55]
	v_pk_mul_f32 v[48:49], v[244:245], v[48:49]
	v_pk_mul_f32 v[50:51], v[246:247], v[50:51]
	v_pk_mul_f32 v[52:53], v[82:83], v[52:53]
	v_pk_mul_f32 v[54:55], v[56:57], v[54:55]
	v_pk_mul_f32 v[48:49], v[58:59], v[48:49]
	v_pk_mul_f32 v[50:51], v[86:87], v[50:51]
	v_cvt_pk_bf16_f32 v52, v52, v53
	v_cvt_pk_bf16_f32 v53, v54, v55
	v_cvt_pk_bf16_f32 v54, v48, v49
	v_cvt_pk_bf16_f32 v55, v50, v51
	global_store_dwordx4 v[70:71], v[52:55], off
	s_nop 1
	s_nop 0
	s_nop 0
	s_nop 0
	v_lshlrev_b32_e32 v2, 16, v44
	v_mul_f32_e32 v0, 0xbfb8aa3b, v2
	v_mul_f32_e32 v58, 0xbfb8aa3b, v3
	v_exp_f32_e32 v0, v0
	v_lshlrev_b32_e32 v44, 16, v45
	v_exp_f32_e32 v58, v58
	v_mul_f32_e32 v59, 0xbfb8aa3b, v44
	v_and_b32_e32 v45, 0xffff0000, v45
	v_exp_f32_e32 v59, v59
	v_mul_f32_e32 v60, 0xbfb8aa3b, v45
	v_add_f32_e32 v0, 1.0, v0
	v_exp_f32_e32 v60, v60
	v_add_f32_e32 v61, 1.0, v58
	v_rcp_f32_e32 v58, v0
	v_mul_f32_e32 v0, 0x4b800000, v68
	v_cmp_gt_f32_e32 vcc, s59, v68
	v_add_f32_e32 v62, 1.0, v59
	v_rcp_f32_e32 v59, v61
	v_cndmask_b32_e32 v0, v68, v0, vcc
	v_rsq_f32_e32 v0, v0
	v_add_f32_e32 v63, 1.0, v60
	v_rcp_f32_e32 v60, v62
	v_rcp_f32_e32 v61, v63
	v_pk_mul_f32 v[2:3], v[58:59], v[2:3]
	v_mul_f32_e32 v58, 0x45800000, v0
	v_cndmask_b32_e32 v0, v0, v58, vcc
	v_pk_mul_f32 v[42:43], v[42:43], v[0:1] op_sel_hi:[1,0]
	v_pk_mul_f32 v[44:45], v[60:61], v[44:45]
	v_pk_mul_f32 v[40:41], v[40:41], v[0:1] op_sel_hi:[1,0]
	v_pk_mul_f32 v[36:37], v[36:37], v[0:1] op_sel_hi:[1,0]
	v_lshlrev_b64 v[56:57], 11, v[124:125]
	v_lshl_add_u64 v[56:57], s[28:29], 0, v[56:57]
	s_nop 0
	v_pk_mul_f32 v[42:43], v[242:243], v[42:43]
	v_pk_mul_f32 v[40:41], v[240:241], v[40:41]
	v_pk_mul_f32 v[42:43], v[44:45], v[42:43]
	v_lshlrev_b32_e32 v44, 16, v46
	v_pk_mul_f32 v[2:3], v[2:3], v[40:41]
	v_mul_f32_e32 v40, 0xbfb8aa3b, v44
	v_and_b32_e32 v45, 0xffff0000, v46
	v_exp_f32_e32 v48, v40
	v_cvt_pk_bf16_f32 v40, v2, v3
	v_mul_f32_e32 v3, 0xbfb8aa3b, v45
	v_exp_f32_e32 v3, v3
	v_cvt_pk_bf16_f32 v41, v42, v43
	v_lshlrev_b32_e32 v42, 16, v47
	v_and_b32_e32 v43, 0xffff0000, v47
	v_add_f32_e32 v2, 1.0, v48
	v_add_f32_e32 v3, 1.0, v3
	v_mul_f32_e32 v46, 0xbfb8aa3b, v42
	v_mul_f32_e32 v47, 0xbfb8aa3b, v43
	v_rcp_f32_e32 v2, v2
	v_rcp_f32_e32 v3, v3
	v_exp_f32_e32 v46, v46
	v_exp_f32_e32 v47, v47
	s_nop 0
	v_pk_mul_f32 v[36:37], v[244:245], v[36:37]
	v_pk_mul_f32 v[2:3], v[2:3], v[44:45]
	v_add_f32_e32 v44, 1.0, v46
	v_add_f32_e32 v45, 1.0, v47
	v_rcp_f32_e32 v44, v44
	v_rcp_f32_e32 v45, v45
	v_pk_mul_f32 v[2:3], v[2:3], v[36:37]
	v_pk_mul_f32 v[36:37], v[38:39], v[0:1] op_sel_hi:[1,0]
	v_pk_mul_f32 v[38:39], v[44:45], v[42:43]
	v_pk_mul_f32 v[36:37], v[246:247], v[36:37]
	v_cvt_pk_bf16_f32 v42, v2, v3
	v_lshl_add_u64 v[2:3], v[56:57], 0, s[38:39]
	v_pk_mul_f32 v[36:37], v[38:39], v[36:37]
	v_lshl_add_u64 v[2:3], v[2:3], 0, v[72:73]
	v_cvt_pk_bf16_f32 v43, v36, v37
	v_lshl_add_u64 v[2:3], v[2:3], 0, v[126:127]
	global_store_dwordx4 v[2:3], v[40:43], off
	s_nop 1
	s_barrier

.LBB0_1634:
	s_or_b64 exec, exec, s[12:13]
	s_lshl_b32 s12, s2, 2
	s_add_u32 s12, s26, s12
	s_addc_u32 s13, s27, 0
	v_lshl_add_u32 v0, v131, 2, s96
	v_lshl_add_u64 v[84:85], v[84:85], 2, s[12:13]
	s_waitcnt lgkmcnt(0)
	s_barrier
	ds_read2st64_b32 v[94:95], v0 offset1:1
	ds_read2st64_b32 v[96:97], v0 offset0:2 offset1:3
	ds_read2st64_b32 v[98:99], v0 offset0:4 offset1:5
	ds_read2st64_b32 v[100:101], v0 offset0:6 offset1:7
	global_load_dwordx4 v[244:247], v[84:85], off offset:16
	global_load_dwordx4 v[240:243], v[84:85], off
	s_waitcnt vmcnt(5)
	v_lshlrev_b32_e32 v104, 16, v72
	v_and_b32_e32 v105, 0xffff0000, v72
	v_mul_f32_e32 v0, 0xbfb8aa3b, v104
	v_exp_f32_e32 v0, v0
	v_mul_f32_e32 v72, 0xbfb8aa3b, v105
	v_exp_f32_e32 v106, v72
	v_and_b32_e32 v107, 0xffff0000, v73
	v_add_f32_e32 v0, 1.0, v0
	v_rcp_f32_e32 v72, v0
	v_add_f32_e32 v0, 1.0, v106
	v_lshlrev_b32_e32 v106, 16, v73
	v_mul_f32_e32 v73, 0xbfb8aa3b, v106
	v_exp_f32_e32 v108, v73
	v_mul_f32_e32 v73, 0xbfb8aa3b, v107
	v_exp_f32_e32 v109, v73
	v_lshlrev_b32_e32 v110, 16, v74
	v_rcp_f32_e32 v73, v0
	v_add_f32_e32 v0, 1.0, v108
	v_and_b32_e32 v111, 0xffff0000, v74
	v_mul_f32_e32 v74, 0xbfb8aa3b, v110
	v_rcp_f32_e32 v108, v0
	v_add_f32_e32 v0, 1.0, v109
	v_exp_f32_e32 v74, v74
	v_mul_f32_e32 v109, 0xbfb8aa3b, v111
	v_exp_f32_e32 v112, v109
	v_rcp_f32_e32 v109, v0
	v_add_f32_e32 v0, 1.0, v74
	v_rcp_f32_e32 v74, v0
	v_add_f32_e32 v0, 1.0, v112
	v_lshlrev_b32_e32 v112, 16, v75
	v_and_b32_e32 v113, 0xffff0000, v75
	v_mul_f32_e32 v75, 0xbfb8aa3b, v112
	v_exp_f32_e32 v114, v75
	v_mul_f32_e32 v75, 0xbfb8aa3b, v113
	v_exp_f32_e32 v115, v75
	v_rcp_f32_e32 v75, v0
	v_add_f32_e32 v0, 1.0, v114
	v_rcp_f32_e32 v114, v0
	v_add_f32_e32 v0, 1.0, v115
	v_rcp_f32_e32 v115, v0
	v_lshl_add_u32 v0, v129, 2, s96
	v_pk_mul_f32 v[106:107], v[108:109], v[106:107]
	v_pk_mul_f32 v[108:109], v[74:75], v[110:111]
	ds_read2st64_b32 v[74:75], v0 offset1:1
	v_pk_mul_f32 v[110:111], v[114:115], v[112:113]
	ds_read2st64_b32 v[112:113], v0 offset0:2 offset1:3
	ds_read2st64_b32 v[114:115], v0 offset0:4 offset1:5
	ds_read2st64_b32 v[116:117], v0 offset0:6 offset1:7
	s_waitcnt lgkmcnt(7)
	v_mov_b32_e32 v119, v94
	v_lshlrev_b64 v[102:103], 11, v[124:125]
	s_waitcnt lgkmcnt(3)
	v_mov_b32_e32 v118, v74
	v_pk_add_f32 v[118:119], v[118:119], 0 op_sel_hi:[1,0]
	v_mov_b32_e32 v94, v75
	v_pk_add_f32 v[74:75], v[118:119], v[94:95]
	s_waitcnt lgkmcnt(2)
	v_mov_b32_e32 v94, v112
	v_mov_b32_e32 v95, v96
	v_pk_add_f32 v[74:75], v[74:75], v[94:95]
	v_mov_b32_e32 v96, v113
	v_pk_add_f32 v[74:75], v[74:75], v[96:97]
	s_waitcnt lgkmcnt(1)
	v_mov_b32_e32 v94, v114
	v_mov_b32_e32 v95, v98
	v_pk_add_f32 v[74:75], v[74:75], v[94:95]
	v_mov_b32_e32 v98, v115
	v_pk_add_f32 v[74:75], v[74:75], v[98:99]
	s_waitcnt lgkmcnt(0)
	v_mov_b32_e32 v94, v116
	v_mov_b32_e32 v95, v100
	v_pk_add_f32 v[74:75], v[74:75], v[94:95]
	v_mov_b32_e32 v100, v117
	v_pk_add_f32 v[94:95], v[74:75], v[100:101]
	v_mov_b64_e32 v[74:75], s[60:61]
	v_pk_fma_f32 v[94:95], v[94:95], s[58:59], v[74:75] op_sel_hi:[1,0,0]
	v_ashrrev_i32_e32 v133, 31, v132
	v_mul_f32_e32 v0, 0x4b800000, v95
	v_cmp_gt_f32_e32 vcc, s59, v95
	v_lshl_add_u64 v[102:103], s[28:29], 0, v[102:103]
	s_lshl_b32 s38, s2, 1
	v_cndmask_b32_e32 v0, v95, v0, vcc
	v_rsq_f32_e32 v0, v0
	v_pk_mul_f32 v[104:105], v[72:73], v[104:105]
	v_lshl_add_u64 v[102:103], v[102:103], 0, s[38:39]
	v_lshlrev_b64 v[72:73], 1, v[132:133]
	v_mul_f32_e32 v95, 0x45800000, v0
	v_cndmask_b32_e32 v0, v0, v95, vcc
	v_pk_mul_f32 v[80:81], v[80:81], v[0:1] op_sel_hi:[1,0]
	v_pk_mul_f32 v[82:83], v[82:83], v[0:1] op_sel_hi:[1,0]
	v_pk_mul_f32 v[76:77], v[76:77], v[0:1] op_sel_hi:[1,0]
	v_pk_mul_f32 v[78:79], v[78:79], v[0:1] op_sel_hi:[1,0]
	s_waitcnt vmcnt(0)
	v_pk_mul_f32 v[80:81], v[240:241], v[80:81]
	v_pk_mul_f32 v[82:83], v[242:243], v[82:83]
	v_pk_mul_f32 v[76:77], v[244:245], v[76:77]
	v_pk_mul_f32 v[78:79], v[246:247], v[78:79]
	v_lshl_add_u64 v[96:97], v[102:103], 0, v[72:73]
	v_mov_b32_e32 v127, v1
	v_pk_mul_f32 v[80:81], v[104:105], v[80:81]
	v_pk_mul_f32 v[82:83], v[106:107], v[82:83]
	v_pk_mul_f32 v[76:77], v[108:109], v[76:77]
	v_pk_mul_f32 v[78:79], v[110:111], v[78:79]
	v_lshl_add_u64 v[96:97], v[96:97], 0, v[126:127]
	v_cvt_pk_bf16_f32 v80, v80, v81
	v_cvt_pk_bf16_f32 v81, v82, v83
	v_cvt_pk_bf16_f32 v82, v76, v77
	v_cvt_pk_bf16_f32 v83, v78, v79
	global_store_dwordx4 v[96:97], v[80:83], off
	s_nop 1
	s_nop 0
	s_nop 0
	s_nop 0
	v_lshlrev_b32_e32 v86, 16, v68
	v_and_b32_e32 v87, 0xffff0000, v68
	v_lshlrev_b32_e32 v68, 16, v69
	v_mul_f32_e32 v0, 0xbfb8aa3b, v86
	v_mul_f32_e32 v92, 0xbfb8aa3b, v68
	v_exp_f32_e32 v0, v0
	v_exp_f32_e32 v92, v92
	v_and_b32_e32 v69, 0xffff0000, v69
	v_lshlrev_b32_e32 v88, 16, v70
	v_and_b32_e32 v89, 0xffff0000, v70
	v_mul_f32_e32 v70, 0xbfb8aa3b, v87
	v_mul_f32_e32 v93, 0xbfb8aa3b, v69
	v_add_f32_e32 v0, 1.0, v0
	v_mul_f32_e32 v96, 0xbfb8aa3b, v89
	v_exp_f32_e32 v70, v70
	v_exp_f32_e32 v93, v93
	v_add_f32_e32 v97, 1.0, v92
	v_rcp_f32_e32 v92, v0
	v_mul_f32_e32 v0, 0x4b800000, v94
	v_cmp_gt_f32_e32 vcc, s59, v94
	v_exp_f32_e32 v96, v96
	v_add_f32_e32 v70, 1.0, v70
	v_cndmask_b32_e32 v0, v94, v0, vcc
	v_rsq_f32_e32 v0, v0
	v_add_f32_e32 v98, 1.0, v93
	v_add_f32_e32 v99, 1.0, v96
	v_rcp_f32_e32 v93, v70
	v_rcp_f32_e32 v96, v97
	v_rcp_f32_e32 v97, v98
	v_mul_f32_e32 v70, 0x45800000, v0
	v_cndmask_b32_e32 v0, v0, v70, vcc
	v_pk_mul_f32 v[64:65], v[64:65], v[0:1] op_sel_hi:[1,0]
	v_pk_mul_f32 v[66:67], v[66:67], v[0:1] op_sel_hi:[1,0]
	v_pk_mul_f32 v[86:87], v[92:93], v[86:87]
	v_pk_mul_f32 v[68:69], v[96:97], v[68:69]
	v_pk_mul_f32 v[60:61], v[60:61], v[0:1] op_sel_hi:[1,0]
	v_mul_f32_e32 v95, 0xbfb8aa3b, v88
	v_exp_f32_e32 v95, v95
	v_rcp_f32_e32 v99, v99
	v_mov_b32_e32 v131, v125
	v_pk_mul_f32 v[62:63], v[62:63], v[0:1] op_sel_hi:[1,0]
	v_add_f32_e32 v95, 1.0, v95
	v_rcp_f32_e32 v98, v95
	v_lshlrev_b64 v[90:91], 11, v[130:131]
	v_lshl_add_u64 v[90:91], s[28:29], 0, v[90:91]
	v_lshl_add_u32 v0, v177, 2, s96
	v_mov_b32_e32 v129, v125
	s_cmpk_gt_i32 s81, 0x3ff
	s_mov_b64 s[12:13], -1
	s_nop 0
	v_pk_mul_f32 v[64:65], v[240:241], v[64:65]
	v_pk_mul_f32 v[66:67], v[242:243], v[66:67]
	s_nop 0
	v_pk_mul_f32 v[76:77], v[244:245], v[60:61]
	v_pk_mul_f32 v[60:61], v[86:87], v[64:65]
	v_pk_mul_f32 v[64:65], v[68:69], v[66:67]
	v_cvt_pk_bf16_f32 v60, v60, v61
	v_cvt_pk_bf16_f32 v61, v64, v65
	v_lshlrev_b32_e32 v64, 16, v71
	v_and_b32_e32 v65, 0xffff0000, v71
	v_mul_f32_e32 v66, 0xbfb8aa3b, v64
	v_exp_f32_e32 v68, v66
	v_mul_f32_e32 v66, 0xbfb8aa3b, v65
	v_exp_f32_e32 v69, v66
	v_pk_mul_f32 v[62:63], v[246:247], v[62:63]
	v_add_f32_e32 v68, 1.0, v68
	v_rcp_f32_e32 v68, v68
	v_add_f32_e32 v69, 1.0, v69
	v_rcp_f32_e32 v69, v69
	v_pk_mul_f32 v[66:67], v[98:99], v[88:89]
	v_lshlrev_b32_e32 v82, 16, v56
	v_pk_mul_f32 v[66:67], v[66:67], v[76:77]
	v_pk_mul_f32 v[64:65], v[68:69], v[64:65]
	v_and_b32_e32 v83, 0xffff0000, v56
	v_pk_mul_f32 v[64:65], v[64:65], v[62:63]
	v_cvt_pk_bf16_f32 v62, v66, v67
	v_cvt_pk_bf16_f32 v63, v64, v65
	v_lshl_add_u64 v[64:65], v[90:91], 0, s[38:39]
	v_lshl_add_u64 v[64:65], v[64:65], 0, v[72:73]
	v_lshl_add_u64 v[64:65], v[64:65], 0, v[126:127]
	global_store_dwordx4 v[64:65], v[60:63], off
	s_nop 1
	ds_read2st64_b32 v[68:69], v0 offset1:1
	ds_read2st64_b32 v[70:71], v0 offset0:2 offset1:3
	ds_read2st64_b32 v[76:77], v0 offset0:4 offset1:5
	ds_read2st64_b32 v[78:79], v0 offset0:6 offset1:7
	s_nop 0
	s_nop 0
	v_mul_f32_e32 v0, 0xbfb8aa3b, v82
	v_exp_f32_e32 v0, v0
	v_mul_f32_e32 v56, 0xbfb8aa3b, v83
	v_exp_f32_e32 v56, v56
	v_and_b32_e32 v89, 0xffff0000, v58
	v_add_f32_e32 v0, 1.0, v0
	v_rcp_f32_e32 v86, v0
	v_add_f32_e32 v0, 1.0, v56
	v_lshlrev_b32_e32 v56, 16, v57
	v_rcp_f32_e32 v87, v0
	v_and_b32_e32 v57, 0xffff0000, v57
	v_mul_f32_e32 v0, 0xbfb8aa3b, v56
	v_exp_f32_e32 v0, v0
	v_mul_f32_e32 v88, 0xbfb8aa3b, v57
	v_exp_f32_e32 v88, v88
	v_pk_mul_f32 v[82:83], v[86:87], v[82:83]
	v_add_f32_e32 v0, 1.0, v0
	v_rcp_f32_e32 v86, v0
	v_add_f32_e32 v0, 1.0, v88
	v_lshlrev_b32_e32 v88, 16, v58
	v_rcp_f32_e32 v87, v0
	v_mul_f32_e32 v0, 0xbfb8aa3b, v88
	v_exp_f32_e32 v0, v0
	v_mul_f32_e32 v58, 0xbfb8aa3b, v89
	v_exp_f32_e32 v90, v58
	v_pk_mul_f32 v[56:57], v[86:87], v[56:57]
	v_lshlrev_b32_e32 v86, 16, v59
	v_add_f32_e32 v0, 1.0, v0
	v_and_b32_e32 v87, 0xffff0000, v59
	v_mul_f32_e32 v59, 0xbfb8aa3b, v86
	v_rcp_f32_e32 v58, v0
	v_add_f32_e32 v0, 1.0, v90
	v_exp_f32_e32 v90, v59
	v_mul_f32_e32 v59, 0xbfb8aa3b, v87
	v_exp_f32_e32 v91, v59
	v_rcp_f32_e32 v59, v0
	v_add_f32_e32 v0, 1.0, v90
	v_rcp_f32_e32 v90, v0
	v_add_f32_e32 v0, 1.0, v91
	v_rcp_f32_e32 v91, v0
	v_lshl_add_u32 v0, v3, 2, s96
	v_pk_mul_f32 v[58:59], v[58:59], v[88:89]
	ds_read2st64_b32 v[88:89], v0 offset1:1
	v_pk_mul_f32 v[86:87], v[90:91], v[86:87]
	ds_read2st64_b32 v[90:91], v0 offset0:2 offset1:3
	ds_read2st64_b32 v[92:93], v0 offset0:4 offset1:5
	ds_read2st64_b32 v[94:95], v0 offset0:6 offset1:7
	s_waitcnt lgkmcnt(7)
	v_mov_b32_e32 v97, v68
	v_lshlrev_b64 v[80:81], 11, v[128:129]
	s_waitcnt lgkmcnt(3)
	v_mov_b32_e32 v96, v88
	v_pk_add_f32 v[96:97], v[96:97], 0 op_sel_hi:[1,0]
	v_mov_b32_e32 v68, v89
	v_pk_add_f32 v[68:69], v[96:97], v[68:69]
	s_waitcnt lgkmcnt(2)
	v_mov_b32_e32 v88, v90
	v_mov_b32_e32 v89, v70
	v_pk_add_f32 v[68:69], v[68:69], v[88:89]
	v_mov_b32_e32 v70, v91
	v_pk_add_f32 v[68:69], v[68:69], v[70:71]
	s_waitcnt lgkmcnt(1)
	v_mov_b32_e32 v70, v92
	v_mov_b32_e32 v71, v76
	v_pk_add_f32 v[68:69], v[68:69], v[70:71]
	v_mov_b32_e32 v76, v93
	v_pk_add_f32 v[68:69], v[68:69], v[76:77]
	s_waitcnt lgkmcnt(0)
	v_mov_b32_e32 v70, v94
	v_mov_b32_e32 v71, v78
	v_pk_add_f32 v[68:69], v[68:69], v[70:71]
	v_mov_b32_e32 v78, v95
	v_pk_add_f32 v[68:69], v[68:69], v[78:79]
	v_lshl_add_u64 v[80:81], s[28:29], 0, v[80:81]
	v_pk_fma_f32 v[68:69], v[68:69], s[58:59], v[74:75] op_sel_hi:[1,0,0]
	v_lshl_add_u64 v[70:71], v[80:81], 0, s[38:39]
	v_mul_f32_e32 v0, 0x4b800000, v69
	v_cmp_gt_f32_e32 vcc, s59, v69
	v_lshl_add_u64 v[70:71], v[70:71], 0, v[72:73]
	v_lshl_add_u64 v[70:71], v[70:71], 0, v[126:127]
	v_cndmask_b32_e32 v0, v69, v0, vcc
	v_rsq_f32_e32 v0, v0
	s_nop 0
	v_mul_f32_e32 v3, 0x45800000, v0
	v_cndmask_b32_e32 v0, v0, v3, vcc
	v_pk_mul_f32 v[52:53], v[52:53], v[0:1] op_sel_hi:[1,0]
	v_pk_mul_f32 v[54:55], v[54:55], v[0:1] op_sel_hi:[1,0]
	v_pk_mul_f32 v[48:49], v[48:49], v[0:1] op_sel_hi:[1,0]
	v_pk_mul_f32 v[50:51], v[50:51], v[0:1] op_sel_hi:[1,0]
	s_nop 0
	v_pk_mul_f32 v[52:53], v[240:241], v[52:53]
	v_pk_mul_f32 v[54:55], v[242:243], v[54:55]
	v_pk_mul_f32 v[48:49], v[244:245], v[48:49]
	v_pk_mul_f32 v[50:51], v[246:247], v[50:51]
	v_pk_mul_f32 v[52:53], v[82:83], v[52:53]
	v_pk_mul_f32 v[54:55], v[56:57], v[54:55]
	v_pk_mul_f32 v[48:49], v[58:59], v[48:49]
	v_pk_mul_f32 v[50:51], v[86:87], v[50:51]
	v_cvt_pk_bf16_f32 v52, v52, v53
	v_cvt_pk_bf16_f32 v53, v54, v55
	v_cvt_pk_bf16_f32 v54, v48, v49
	v_cvt_pk_bf16_f32 v55, v50, v51
	global_store_dwordx4 v[70:71], v[52:55], off
	s_nop 1
	s_nop 0
	s_nop 0
	s_nop 0
	v_lshlrev_b32_e32 v56, 16, v44
	v_and_b32_e32 v57, 0xffff0000, v44
	v_lshlrev_b32_e32 v44, 16, v45
	v_mul_f32_e32 v0, 0xbfb8aa3b, v56
	v_mul_f32_e32 v60, 0xbfb8aa3b, v44
	v_exp_f32_e32 v0, v0
	v_exp_f32_e32 v60, v60
	v_and_b32_e32 v45, 0xffff0000, v45
	v_mul_f32_e32 v61, 0xbfb8aa3b, v45
	v_add_f32_e32 v0, 1.0, v0
	v_mul_f32_e32 v59, 0xbfb8aa3b, v57
	v_exp_f32_e32 v61, v61
	v_add_f32_e32 v62, 1.0, v60
	v_rcp_f32_e32 v60, v0
	v_mul_f32_e32 v0, 0x4b800000, v68
	v_cmp_gt_f32_e32 vcc, s59, v68
	v_exp_f32_e32 v59, v59
	v_add_f32_e32 v63, 1.0, v61
	v_cndmask_b32_e32 v0, v68, v0, vcc
	v_rsq_f32_e32 v0, v0
	v_add_f32_e32 v59, 1.0, v59
	v_rcp_f32_e32 v62, v62
	v_rcp_f32_e32 v63, v63
	v_rcp_f32_e32 v61, v59
	v_mul_f32_e32 v59, 0x45800000, v0
	v_cndmask_b32_e32 v0, v0, v59, vcc
	v_pk_mul_f32 v[42:43], v[42:43], v[0:1] op_sel_hi:[1,0]
	v_lshlrev_b32_e32 v58, 16, v46
	v_pk_mul_f32 v[44:45], v[62:63], v[44:45]
	v_pk_mul_f32 v[40:41], v[40:41], v[0:1] op_sel_hi:[1,0]
	v_pk_mul_f32 v[56:57], v[60:61], v[56:57]
	v_and_b32_e32 v59, 0xffff0000, v46
	v_mov_b32_e32 v3, v125
	v_lshlrev_b64 v[2:3], 11, v[2:3]
	v_pk_mul_f32 v[36:37], v[36:37], v[0:1] op_sel_hi:[1,0]
	v_lshl_add_u64 v[2:3], s[28:29], 0, v[2:3]
	v_pk_mul_f32 v[38:39], v[38:39], v[0:1] op_sel_hi:[1,0]
	v_lshl_add_u64 v[2:3], v[2:3], 0, s[38:39]
	v_lshl_add_u64 v[2:3], v[2:3], 0, v[72:73]
	v_lshl_add_u64 v[2:3], v[2:3], 0, v[126:127]
	s_nop 0
	v_pk_mul_f32 v[42:43], v[242:243], v[42:43]
	s_nop 0
	v_pk_mul_f32 v[42:43], v[44:45], v[42:43]
	v_mul_f32_e32 v44, 0xbfb8aa3b, v58
	v_exp_f32_e32 v44, v44
	v_pk_mul_f32 v[40:41], v[240:241], v[40:41]
	v_and_b32_e32 v45, 0xffff0000, v47
	v_pk_mul_f32 v[40:41], v[56:57], v[40:41]
	s_nop 0
	v_pk_mul_f32 v[36:37], v[244:245], v[36:37]
	v_cvt_pk_bf16_f32 v40, v40, v41
	v_cvt_pk_bf16_f32 v41, v42, v43
	v_add_f32_e32 v42, 1.0, v44
	v_mul_f32_e32 v43, 0xbfb8aa3b, v59
	v_lshlrev_b32_e32 v44, 16, v47
	v_exp_f32_e32 v43, v43
	v_mul_f32_e32 v46, 0xbfb8aa3b, v44
	v_mul_f32_e32 v47, 0xbfb8aa3b, v45
	v_exp_f32_e32 v46, v46
	v_exp_f32_e32 v47, v47
	v_add_f32_e32 v43, 1.0, v43
	v_rcp_f32_e32 v42, v42
	v_rcp_f32_e32 v43, v43
	v_add_f32_e32 v46, 1.0, v46
	v_add_f32_e32 v47, 1.0, v47
	v_rcp_f32_e32 v46, v46
	v_rcp_f32_e32 v47, v47
	v_pk_mul_f32 v[42:43], v[42:43], v[58:59]
	v_pk_mul_f32 v[38:39], v[246:247], v[38:39]
	v_pk_mul_f32 v[36:37], v[42:43], v[36:37]
	v_pk_mul_f32 v[42:43], v[46:47], v[44:45]
	s_nop 0
	v_pk_mul_f32 v[38:39], v[42:43], v[38:39]
	v_cvt_pk_bf16_f32 v42, v36, v37
	v_cvt_pk_bf16_f32 v43, v38, v39
	global_store_dwordx4 v[2:3], v[40:43], off
	s_nop 1
	s_barrier
	s_cbranch_scc1 .LBB0_1595
	s_add_i32 s2, s74, s82
	s_cmpk_gt_i32 s2, 0x3ff
	s_cbranch_scc1 .LBB0_1637
	v_mov_b32_e32 v0, v204
	s_ashr_i32 s12, s2, 8
	v_ashrrev_i32_e32 v2, 31, v0
	v_lshrrev_b32_e32 v2, 27, v2
	v_add_u32_e32 v3, v0, v2
	s_ashr_i32 s13, s12, 31
	s_add_i32 s2, s75, s80
	v_ashrrev_i32_e32 v2, 5, v3
	v_and_b32_e32 v3, 0x1fffffe0, v3
	s_lshl_b64 s[12:13], s[12:13], 12
	s_and_b32 s2, s2, 0xfc0
	v_sub_u32_e32 v3, v0, v3
	s_or_b32 s12, s12, s2
	v_lshlrev_b32_e32 v4, 3, v3
	v_ashrrev_i32_e32 v3, 31, v2
	s_add_i32 s2, s76, s79
	v_lshl_add_u64 v[2:3], s[12:13], 0, v[2:3]
	v_mov_b64_e32 v[20:21], s[30:31]
	s_and_b32 s2, s2, 0x300
	v_mad_u64_u32 v[6:7], s[14:15], v2, s33, v[20:21]
	v_mad_i32_i24 v7, v3, s33, v7
	s_lshl_b32 s38, s2, 1
	v_lshl_add_u64 v[2:3], v[6:7], 0, s[38:39]
	v_ashrrev_i32_e32 v5, 31, v4
	v_lshl_add_u64 v[2:3], v[4:5], 1, v[2:3]
	v_add_u32_e32 v5, 0x200, v0
	v_ashrrev_i32_e32 v4, 31, v5
	v_lshrrev_b32_e32 v4, 27, v4
	v_add_u32_e32 v6, v5, v4
	v_ashrrev_i32_e32 v4, 5, v6
	v_and_b32_e32 v6, 0x1fffffe0, v6
	v_sub_u32_e32 v5, v5, v6
	v_lshlrev_b32_e32 v6, 3, v5
	v_ashrrev_i32_e32 v5, 31, v4
	v_lshl_add_u64 v[4:5], s[12:13], 0, v[4:5]
	v_mad_u64_u32 v[8:9], s[14:15], v4, s33, v[20:21]
	v_mad_i32_i24 v9, v5, s33, v9
	v_add_co_u32_e32 v2, vcc, s34, v2
	v_lshl_add_u64 v[4:5], v[8:9], 0, s[38:39]
	v_ashrrev_i32_e32 v7, 31, v6
	v_addc_co_u32_e32 v3, vcc, 0, v3, vcc
	v_lshl_add_u64 v[4:5], v[6:7], 1, v[4:5]
	v_add_co_u32_e32 v8, vcc, s34, v4
	s_nop 1
	v_addc_co_u32_e32 v9, vcc, 0, v5, vcc
	global_load_dwordx4 v[4:7], v[2:3], off offset:2048
	s_nop 0
	global_load_dwordx4 v[8:11], v[8:9], off offset:2048
	v_add_u32_e32 v3, 0x400, v0
	v_ashrrev_i32_e32 v2, 31, v3
	v_lshrrev_b32_e32 v2, 27, v2
	v_add_u32_e32 v22, v3, v2
	v_ashrrev_i32_e32 v2, 5, v22
	v_and_b32_e32 v22, 0x1fffffe0, v22
	v_sub_u32_e32 v3, v3, v22
	v_lshlrev_b32_e32 v22, 3, v3
	v_ashrrev_i32_e32 v3, 31, v2
	v_lshl_add_u64 v[2:3], s[12:13], 0, v[2:3]
	v_mad_u64_u32 v[24:25], s[14:15], v2, s33, v[20:21]
	v_mad_i32_i24 v25, v3, s33, v25
	v_lshl_add_u64 v[2:3], v[24:25], 0, s[38:39]
	v_ashrrev_i32_e32 v23, 31, v22
	v_add_u32_e32 v0, 0x600, v0
	v_lshl_add_u64 v[2:3], v[22:23], 1, v[2:3]
	v_ashrrev_i32_e32 v22, 31, v0
	v_lshrrev_b32_e32 v22, 27, v22
	v_add_u32_e32 v23, v0, v22
	v_ashrrev_i32_e32 v22, 5, v23
	v_and_b32_e32 v23, 0x1fffffe0, v23
	v_sub_u32_e32 v0, v0, v23
	v_ashrrev_i32_e32 v23, 31, v22
	v_lshl_add_u64 v[22:23], s[12:13], 0, v[22:23]
	v_mad_u64_u32 v[20:21], s[12:13], v22, s33, v[20:21]
	v_lshlrev_b32_e32 v24, 3, v0
	v_mad_i32_i24 v21, v23, s33, v21
	v_add_co_u32_e32 v2, vcc, s34, v2
	v_lshl_add_u64 v[20:21], v[20:21], 0, s[38:39]
	v_ashrrev_i32_e32 v25, 31, v24
	v_addc_co_u32_e32 v3, vcc, 0, v3, vcc
	v_lshl_add_u64 v[20:21], v[24:25], 1, v[20:21]
	v_add_co_u32_e32 v24, vcc, 0x7a00000, v20
	s_nop 1
	v_addc_co_u32_e32 v25, vcc, 0, v21, vcc
	global_load_dwordx4 v[20:23], v[2:3], off offset:2048
	s_nop 0
	global_load_dwordx4 v[24:27], v[24:25], off offset:2048

.LBB0_1737:
	s_or_b64 exec, exec, s[8:9]
	s_add_i32 s49, s47, s22
	s_lshl_b32 s8, s2, 2
	s_add_u32 s8, s26, s8
	s_addc_u32 s9, s27, 0
	v_lshl_add_u32 v8, v131, 2, s96
	v_lshl_add_u64 v[84:85], v[84:85], 2, s[8:9]
	s_waitcnt lgkmcnt(0)
	s_barrier
	ds_read2st64_b32 v[94:95], v8 offset1:1
	ds_read2st64_b32 v[96:97], v8 offset0:2 offset1:3
	ds_read2st64_b32 v[98:99], v8 offset0:4 offset1:5
	ds_read2st64_b32 v[100:101], v8 offset0:6 offset1:7
	global_load_dwordx4 v[244:247], v[84:85], off offset:16
	global_load_dwordx4 v[240:243], v[84:85], off
	s_waitcnt vmcnt(5)
	v_lshlrev_b32_e32 v104, 16, v72
	v_and_b32_e32 v105, 0xffff0000, v72
	v_mul_f32_e32 v8, 0xbfb8aa3b, v104
	v_lshlrev_b64 v[102:103], 11, v[10:11]
	v_exp_f32_e32 v8, v8
	v_mul_f32_e32 v10, 0xbfb8aa3b, v105
	v_exp_f32_e32 v10, v10
	v_lshlrev_b32_e32 v106, 16, v73
	v_add_f32_e32 v8, 1.0, v8
	v_rcp_f32_e32 v72, v8
	v_add_f32_e32 v8, 1.0, v10
	v_mul_f32_e32 v10, 0xbfb8aa3b, v106
	v_exp_f32_e32 v10, v10
	v_and_b32_e32 v107, 0xffff0000, v73
	v_mul_f32_e32 v73, 0xbfb8aa3b, v107
	v_lshlrev_b32_e32 v110, 16, v74
	v_exp_f32_e32 v109, v73
	v_rcp_f32_e32 v73, v8
	v_add_f32_e32 v8, 1.0, v10
	v_and_b32_e32 v111, 0xffff0000, v74
	v_mul_f32_e32 v10, 0xbfb8aa3b, v110
	v_exp_f32_e32 v10, v10
	v_mul_f32_e32 v74, 0xbfb8aa3b, v111
	v_exp_f32_e32 v112, v74
	v_rcp_f32_e32 v108, v8
	v_add_f32_e32 v8, 1.0, v109
	v_rcp_f32_e32 v109, v8
	v_add_f32_e32 v8, 1.0, v10
	v_rcp_f32_e32 v74, v8
	v_add_f32_e32 v8, 1.0, v112
	v_lshlrev_b32_e32 v112, 16, v75
	v_and_b32_e32 v113, 0xffff0000, v75
	v_mul_f32_e32 v10, 0xbfb8aa3b, v112
	v_exp_f32_e32 v10, v10
	v_mul_f32_e32 v75, 0xbfb8aa3b, v113
	v_exp_f32_e32 v115, v75
	v_rcp_f32_e32 v75, v8
	v_add_f32_e32 v8, 1.0, v10
	v_rcp_f32_e32 v114, v8
	v_add_f32_e32 v8, 1.0, v115
	v_rcp_f32_e32 v115, v8
	v_lshl_add_u32 v8, v129, 2, s96
	v_pk_mul_f32 v[106:107], v[108:109], v[106:107]
	v_pk_mul_f32 v[108:109], v[74:75], v[110:111]
	ds_read2st64_b32 v[74:75], v8 offset1:1
	v_pk_mul_f32 v[110:111], v[114:115], v[112:113]
	ds_read2st64_b32 v[112:113], v8 offset0:2 offset1:3
	ds_read2st64_b32 v[114:115], v8 offset0:4 offset1:5
	ds_read2st64_b32 v[116:117], v8 offset0:6 offset1:7
	s_waitcnt lgkmcnt(7)
	v_mov_b32_e32 v119, v94
	v_ashrrev_i32_e32 v133, 31, v132
	s_waitcnt lgkmcnt(3)
	v_mov_b32_e32 v118, v74
	v_pk_add_f32 v[118:119], v[118:119], 0 op_sel_hi:[1,0]
	v_mov_b32_e32 v94, v75
	v_pk_add_f32 v[74:75], v[118:119], v[94:95]
	s_waitcnt lgkmcnt(2)
	v_mov_b32_e32 v94, v112
	v_mov_b32_e32 v95, v96
	v_pk_add_f32 v[74:75], v[74:75], v[94:95]
	v_mov_b32_e32 v96, v113
	v_pk_add_f32 v[74:75], v[74:75], v[96:97]
	s_waitcnt lgkmcnt(1)
	v_mov_b32_e32 v94, v114
	v_mov_b32_e32 v95, v98
	v_pk_add_f32 v[74:75], v[74:75], v[94:95]
	v_mov_b32_e32 v98, v115
	v_pk_add_f32 v[74:75], v[74:75], v[98:99]
	s_waitcnt lgkmcnt(0)
	v_mov_b32_e32 v94, v116
	v_mov_b32_e32 v95, v100
	v_pk_add_f32 v[74:75], v[74:75], v[94:95]
	v_mov_b32_e32 v100, v117
	v_pk_add_f32 v[94:95], v[74:75], v[100:101]
	v_mov_b64_e32 v[74:75], s[48:49]
	v_pk_fma_f32 v[94:95], v[94:95], s[46:47], v[74:75] op_sel_hi:[1,0,0]
	v_lshl_add_u64 v[102:103], s[28:29], 0, v[102:103]
	v_mul_f32_e32 v8, 0x4b800000, v95
	v_cmp_gt_f32_e32 vcc, s45, v95
	s_lshl_b32 s38, s2, 1
	v_pk_mul_f32 v[104:105], v[72:73], v[104:105]
	v_cndmask_b32_e32 v8, v95, v8, vcc
	v_rsq_f32_e32 v8, v8
	v_lshl_add_u64 v[102:103], v[102:103], 0, s[38:39]
	v_lshlrev_b64 v[72:73], 1, v[132:133]
	v_lshl_add_u64 v[96:97], v[102:103], 0, v[72:73]
	v_mul_f32_e32 v10, 0x45800000, v8
	v_cndmask_b32_e32 v8, v8, v10, vcc
	v_pk_mul_f32 v[80:81], v[80:81], v[8:9] op_sel_hi:[1,0]
	v_pk_mul_f32 v[82:83], v[82:83], v[8:9] op_sel_hi:[1,0]
	v_pk_mul_f32 v[76:77], v[76:77], v[8:9] op_sel_hi:[1,0]
	v_pk_mul_f32 v[78:79], v[78:79], v[8:9] op_sel_hi:[1,0]
	s_waitcnt vmcnt(0)
	v_pk_mul_f32 v[80:81], v[240:241], v[80:81]
	v_pk_mul_f32 v[82:83], v[242:243], v[82:83]
	v_pk_mul_f32 v[76:77], v[244:245], v[76:77]
	v_pk_mul_f32 v[78:79], v[246:247], v[78:79]
	v_mov_b32_e32 v127, v9
	v_pk_mul_f32 v[80:81], v[104:105], v[80:81]
	v_pk_mul_f32 v[82:83], v[106:107], v[82:83]
	v_pk_mul_f32 v[76:77], v[108:109], v[76:77]
	v_pk_mul_f32 v[78:79], v[110:111], v[78:79]
	v_lshl_add_u64 v[96:97], v[96:97], 0, v[126:127]
	v_cvt_pk_bf16_f32 v80, v80, v81
	v_cvt_pk_bf16_f32 v81, v82, v83
	v_cvt_pk_bf16_f32 v82, v76, v77
	v_cvt_pk_bf16_f32 v83, v78, v79
	global_store_dwordx4 v[96:97], v[80:83], off
	s_nop 1
	s_nop 0
	s_nop 0
	s_nop 0
	v_lshlrev_b32_e32 v86, 16, v68
	v_and_b32_e32 v87, 0xffff0000, v68
	v_lshlrev_b32_e32 v68, 16, v69
	v_and_b32_e32 v69, 0xffff0000, v69
	v_mul_f32_e32 v8, 0xbfb8aa3b, v86
	v_mul_f32_e32 v92, 0xbfb8aa3b, v69
	v_exp_f32_e32 v8, v8
	v_exp_f32_e32 v92, v92
	v_lshlrev_b32_e32 v88, 16, v70
	v_and_b32_e32 v89, 0xffff0000, v70
	v_mul_f32_e32 v10, 0xbfb8aa3b, v87
	v_mul_f32_e32 v70, 0xbfb8aa3b, v68
	v_add_f32_e32 v8, 1.0, v8
	v_mul_f32_e32 v93, 0xbfb8aa3b, v88
	v_exp_f32_e32 v10, v10
	v_exp_f32_e32 v70, v70
	v_add_f32_e32 v97, 1.0, v92
	v_rcp_f32_e32 v92, v8
	v_mul_f32_e32 v8, 0x4b800000, v94
	v_cmp_gt_f32_e32 vcc, s45, v94
	v_exp_f32_e32 v93, v93
	v_add_f32_e32 v10, 1.0, v10
	v_cndmask_b32_e32 v8, v94, v8, vcc
	v_rsq_f32_e32 v8, v8
	v_add_f32_e32 v70, 1.0, v70
	v_add_f32_e32 v98, 1.0, v93
	v_rcp_f32_e32 v93, v10
	v_rcp_f32_e32 v96, v70
	v_rcp_f32_e32 v97, v97
	v_mul_f32_e32 v10, 0x45800000, v8
	v_cndmask_b32_e32 v8, v8, v10, vcc
	v_pk_mul_f32 v[64:65], v[64:65], v[8:9] op_sel_hi:[1,0]
	v_pk_mul_f32 v[66:67], v[66:67], v[8:9] op_sel_hi:[1,0]
	v_pk_mul_f32 v[86:87], v[92:93], v[86:87]
	v_pk_mul_f32 v[68:69], v[96:97], v[68:69]
	v_pk_mul_f32 v[60:61], v[60:61], v[8:9] op_sel_hi:[1,0]
	v_mul_f32_e32 v95, 0xbfb8aa3b, v89
	v_exp_f32_e32 v95, v95
	v_rcp_f32_e32 v94, v98
	v_mov_b32_e32 v131, v11
	v_pk_mul_f32 v[62:63], v[62:63], v[8:9] op_sel_hi:[1,0]
	v_add_f32_e32 v95, 1.0, v95
	v_rcp_f32_e32 v95, v95
	v_lshlrev_b64 v[90:91], 11, v[130:131]
	v_lshl_add_u64 v[90:91], s[28:29], 0, v[90:91]
	v_lshl_add_u32 v8, v177, 2, s96
	v_mov_b32_e32 v129, v11
	s_add_i32 s3, s3, s88
	s_add_i32 s72, s72, s83
	s_cmpk_gt_i32 s49, 0x3ff
	s_cselect_b64 s[8:9], -1, 0
	s_nop 0
	v_pk_mul_f32 v[64:65], v[240:241], v[64:65]
	v_pk_mul_f32 v[66:67], v[242:243], v[66:67]
	s_nop 0
	v_pk_mul_f32 v[76:77], v[244:245], v[60:61]
	v_pk_mul_f32 v[60:61], v[86:87], v[64:65]
	v_pk_mul_f32 v[64:65], v[68:69], v[66:67]
	v_cvt_pk_bf16_f32 v60, v60, v61
	v_cvt_pk_bf16_f32 v61, v64, v65
	v_lshlrev_b32_e32 v64, 16, v71
	v_and_b32_e32 v65, 0xffff0000, v71
	v_mul_f32_e32 v10, 0xbfb8aa3b, v64
	v_exp_f32_e32 v10, v10
	v_mul_f32_e32 v66, 0xbfb8aa3b, v65
	v_exp_f32_e32 v69, v66
	v_pk_mul_f32 v[62:63], v[246:247], v[62:63]
	v_add_f32_e32 v10, 1.0, v10
	v_rcp_f32_e32 v68, v10
	v_add_f32_e32 v10, 1.0, v69
	v_rcp_f32_e32 v69, v10
	v_pk_mul_f32 v[66:67], v[94:95], v[88:89]
	v_lshlrev_b32_e32 v82, 16, v56
	v_pk_mul_f32 v[66:67], v[66:67], v[76:77]
	v_pk_mul_f32 v[64:65], v[68:69], v[64:65]
	v_and_b32_e32 v83, 0xffff0000, v56
	v_pk_mul_f32 v[64:65], v[64:65], v[62:63]
	v_cvt_pk_bf16_f32 v62, v66, v67
	v_cvt_pk_bf16_f32 v63, v64, v65
	v_lshl_add_u64 v[64:65], v[90:91], 0, s[38:39]
	v_lshl_add_u64 v[64:65], v[64:65], 0, v[72:73]
	v_lshl_add_u64 v[64:65], v[64:65], 0, v[126:127]
	global_store_dwordx4 v[64:65], v[60:63], off
	s_nop 1
	ds_read2st64_b32 v[68:69], v8 offset1:1
	ds_read2st64_b32 v[70:71], v8 offset0:2 offset1:3
	ds_read2st64_b32 v[76:77], v8 offset0:4 offset1:5
	ds_read2st64_b32 v[78:79], v8 offset0:6 offset1:7
	s_nop 0
	s_nop 0
	v_mul_f32_e32 v8, 0xbfb8aa3b, v82
	v_exp_f32_e32 v8, v8
	v_mul_f32_e32 v10, 0xbfb8aa3b, v83
	v_exp_f32_e32 v10, v10
	v_lshlrev_b32_e32 v56, 16, v57
	v_add_f32_e32 v8, 1.0, v8
	v_rcp_f32_e32 v86, v8
	v_add_f32_e32 v8, 1.0, v10
	v_rcp_f32_e32 v87, v8
	v_and_b32_e32 v57, 0xffff0000, v57
	v_mul_f32_e32 v8, 0xbfb8aa3b, v56
	v_exp_f32_e32 v8, v8
	v_mul_f32_e32 v10, 0xbfb8aa3b, v57
	v_exp_f32_e32 v10, v10
	v_pk_mul_f32 v[82:83], v[86:87], v[82:83]
	v_add_f32_e32 v8, 1.0, v8
	v_rcp_f32_e32 v86, v8
	v_add_f32_e32 v8, 1.0, v10
	v_lshlrev_b32_e32 v88, 16, v58
	v_rcp_f32_e32 v87, v8
	v_and_b32_e32 v89, 0xffff0000, v58
	v_mul_f32_e32 v8, 0xbfb8aa3b, v88
	v_exp_f32_e32 v8, v8
	v_mul_f32_e32 v10, 0xbfb8aa3b, v89
	v_exp_f32_e32 v10, v10
	v_pk_mul_f32 v[56:57], v[86:87], v[56:57]
	v_add_f32_e32 v8, 1.0, v8
	v_lshlrev_b32_e32 v86, 16, v59
	v_rcp_f32_e32 v58, v8
	v_add_f32_e32 v8, 1.0, v10
	v_and_b32_e32 v87, 0xffff0000, v59
	v_mul_f32_e32 v10, 0xbfb8aa3b, v86
	v_exp_f32_e32 v10, v10
	v_mul_f32_e32 v59, 0xbfb8aa3b, v87
	v_exp_f32_e32 v91, v59
	v_rcp_f32_e32 v59, v8
	v_add_f32_e32 v8, 1.0, v10
	v_rcp_f32_e32 v90, v8
	v_add_f32_e32 v8, 1.0, v91
	v_rcp_f32_e32 v91, v8
	v_lshl_add_u32 v8, v125, 2, s96
	v_pk_mul_f32 v[58:59], v[58:59], v[88:89]
	ds_read2st64_b32 v[88:89], v8 offset1:1
	v_pk_mul_f32 v[86:87], v[90:91], v[86:87]
	ds_read2st64_b32 v[90:91], v8 offset0:2 offset1:3
	ds_read2st64_b32 v[92:93], v8 offset0:4 offset1:5
	ds_read2st64_b32 v[94:95], v8 offset0:6 offset1:7
	s_waitcnt lgkmcnt(7)
	v_mov_b32_e32 v97, v68
	v_lshlrev_b64 v[80:81], 11, v[128:129]
	s_waitcnt lgkmcnt(3)
	v_mov_b32_e32 v96, v88
	v_pk_add_f32 v[96:97], v[96:97], 0 op_sel_hi:[1,0]
	v_mov_b32_e32 v68, v89
	v_pk_add_f32 v[68:69], v[96:97], v[68:69]
	s_waitcnt lgkmcnt(2)
	v_mov_b32_e32 v88, v90
	v_mov_b32_e32 v89, v70
	v_pk_add_f32 v[68:69], v[68:69], v[88:89]
	v_mov_b32_e32 v70, v91
	v_pk_add_f32 v[68:69], v[68:69], v[70:71]
	s_waitcnt lgkmcnt(1)
	v_mov_b32_e32 v70, v92
	v_mov_b32_e32 v71, v76
	v_pk_add_f32 v[68:69], v[68:69], v[70:71]
	v_mov_b32_e32 v76, v93
	v_pk_add_f32 v[68:69], v[68:69], v[76:77]
	s_waitcnt lgkmcnt(0)
	v_mov_b32_e32 v70, v94
	v_mov_b32_e32 v71, v78
	v_pk_add_f32 v[68:69], v[68:69], v[70:71]
	v_mov_b32_e32 v78, v95
	v_pk_add_f32 v[68:69], v[68:69], v[78:79]
	v_lshl_add_u64 v[80:81], s[28:29], 0, v[80:81]
	v_pk_fma_f32 v[68:69], v[68:69], s[46:47], v[74:75] op_sel_hi:[1,0,0]
	v_lshl_add_u64 v[70:71], v[80:81], 0, s[38:39]
	v_mul_f32_e32 v8, 0x4b800000, v69
	v_cmp_gt_f32_e32 vcc, s45, v69
	v_lshl_add_u64 v[70:71], v[70:71], 0, v[72:73]
	v_lshl_add_u64 v[70:71], v[70:71], 0, v[126:127]
	v_cndmask_b32_e32 v8, v69, v8, vcc
	v_rsq_f32_e32 v8, v8
	v_mov_b32_e32 v125, v11
	v_and_b32_e32 v11, 0xffff0000, v44
	v_mul_f32_e32 v10, 0x45800000, v8
	v_cndmask_b32_e32 v8, v8, v10, vcc
	v_pk_mul_f32 v[52:53], v[52:53], v[8:9] op_sel_hi:[1,0]
	v_pk_mul_f32 v[54:55], v[54:55], v[8:9] op_sel_hi:[1,0]
	v_pk_mul_f32 v[48:49], v[48:49], v[8:9] op_sel_hi:[1,0]
	v_pk_mul_f32 v[50:51], v[50:51], v[8:9] op_sel_hi:[1,0]
	s_nop 0
	v_pk_mul_f32 v[52:53], v[240:241], v[52:53]
	v_pk_mul_f32 v[54:55], v[242:243], v[54:55]
	v_pk_mul_f32 v[48:49], v[244:245], v[48:49]
	v_pk_mul_f32 v[50:51], v[246:247], v[50:51]
	v_pk_mul_f32 v[52:53], v[82:83], v[52:53]
	v_pk_mul_f32 v[54:55], v[56:57], v[54:55]
	v_pk_mul_f32 v[48:49], v[58:59], v[48:49]
	v_pk_mul_f32 v[50:51], v[86:87], v[50:51]
	v_cvt_pk_bf16_f32 v52, v52, v53
	v_cvt_pk_bf16_f32 v53, v54, v55
	v_cvt_pk_bf16_f32 v54, v48, v49
	v_cvt_pk_bf16_f32 v55, v50, v51
	global_store_dwordx4 v[70:71], v[52:55], off
	s_nop 1
	s_nop 0
	s_nop 0
	s_nop 0
	v_lshlrev_b32_e32 v10, 16, v44
	v_mul_f32_e32 v8, 0xbfb8aa3b, v10
	v_mul_f32_e32 v58, 0xbfb8aa3b, v11
	v_exp_f32_e32 v8, v8
	v_lshlrev_b32_e32 v44, 16, v45
	v_exp_f32_e32 v58, v58
	v_mul_f32_e32 v59, 0xbfb8aa3b, v44
	v_and_b32_e32 v45, 0xffff0000, v45
	v_exp_f32_e32 v59, v59
	v_mul_f32_e32 v60, 0xbfb8aa3b, v45
	v_add_f32_e32 v8, 1.0, v8
	v_exp_f32_e32 v60, v60
	v_add_f32_e32 v61, 1.0, v58
	v_rcp_f32_e32 v58, v8
	v_mul_f32_e32 v8, 0x4b800000, v68
	v_cmp_gt_f32_e32 vcc, s45, v68
	v_add_f32_e32 v62, 1.0, v59
	v_rcp_f32_e32 v59, v61
	v_cndmask_b32_e32 v8, v68, v8, vcc
	v_rsq_f32_e32 v8, v8
	v_add_f32_e32 v63, 1.0, v60
	v_rcp_f32_e32 v60, v62
	v_rcp_f32_e32 v61, v63
	v_pk_mul_f32 v[10:11], v[58:59], v[10:11]
	v_mul_f32_e32 v58, 0x45800000, v8
	v_cndmask_b32_e32 v8, v8, v58, vcc
	v_pk_mul_f32 v[42:43], v[42:43], v[8:9] op_sel_hi:[1,0]
	v_pk_mul_f32 v[44:45], v[60:61], v[44:45]
	v_pk_mul_f32 v[40:41], v[40:41], v[8:9] op_sel_hi:[1,0]
	v_pk_mul_f32 v[36:37], v[36:37], v[8:9] op_sel_hi:[1,0]
	v_lshlrev_b64 v[56:57], 11, v[124:125]
	v_lshl_add_u64 v[56:57], s[28:29], 0, v[56:57]
	s_nop 0
	v_pk_mul_f32 v[42:43], v[242:243], v[42:43]
	v_pk_mul_f32 v[40:41], v[240:241], v[40:41]
	v_pk_mul_f32 v[42:43], v[44:45], v[42:43]
	v_lshlrev_b32_e32 v44, 16, v46
	v_pk_mul_f32 v[10:11], v[10:11], v[40:41]
	v_mul_f32_e32 v40, 0xbfb8aa3b, v44
	v_and_b32_e32 v45, 0xffff0000, v46
	v_exp_f32_e32 v48, v40
	v_cvt_pk_bf16_f32 v40, v10, v11
	v_mul_f32_e32 v11, 0xbfb8aa3b, v45
	v_exp_f32_e32 v11, v11
	v_cvt_pk_bf16_f32 v41, v42, v43
	v_lshlrev_b32_e32 v42, 16, v47
	v_and_b32_e32 v43, 0xffff0000, v47
	v_add_f32_e32 v10, 1.0, v48
	v_add_f32_e32 v11, 1.0, v11
	v_mul_f32_e32 v46, 0xbfb8aa3b, v42
	v_mul_f32_e32 v47, 0xbfb8aa3b, v43
	v_rcp_f32_e32 v10, v10
	v_rcp_f32_e32 v11, v11
	v_exp_f32_e32 v46, v46
	v_exp_f32_e32 v47, v47
	s_nop 0
	v_pk_mul_f32 v[36:37], v[244:245], v[36:37]
	v_pk_mul_f32 v[10:11], v[10:11], v[44:45]
	v_add_f32_e32 v44, 1.0, v46
	v_add_f32_e32 v45, 1.0, v47
	v_rcp_f32_e32 v44, v44
	v_rcp_f32_e32 v45, v45
	v_pk_mul_f32 v[10:11], v[10:11], v[36:37]
	v_pk_mul_f32 v[36:37], v[38:39], v[8:9] op_sel_hi:[1,0]
	v_pk_mul_f32 v[38:39], v[44:45], v[42:43]
	v_pk_mul_f32 v[36:37], v[246:247], v[36:37]
	v_cvt_pk_bf16_f32 v42, v10, v11
	v_lshl_add_u64 v[10:11], v[56:57], 0, s[38:39]
	v_pk_mul_f32 v[36:37], v[38:39], v[36:37]
	v_lshl_add_u64 v[10:11], v[10:11], 0, v[72:73]
	v_cvt_pk_bf16_f32 v43, v36, v37
	v_lshl_add_u64 v[10:11], v[10:11], 0, v[126:127]
	global_store_dwordx4 v[10:11], v[40:43], off
	s_nop 1
	s_barrier

.LBB0_1777:
	s_or_b64 exec, exec, s[8:9]
	s_lshl_b32 s8, s2, 2
	s_add_u32 s8, s26, s8
	s_addc_u32 s9, s27, 0
	v_lshl_add_u32 v8, v131, 2, s96
	v_lshl_add_u64 v[84:85], v[84:85], 2, s[8:9]
	s_waitcnt lgkmcnt(0)
	s_barrier
	ds_read2st64_b32 v[94:95], v8 offset1:1
	ds_read2st64_b32 v[96:97], v8 offset0:2 offset1:3
	ds_read2st64_b32 v[98:99], v8 offset0:4 offset1:5
	ds_read2st64_b32 v[100:101], v8 offset0:6 offset1:7
	global_load_dwordx4 v[244:247], v[84:85], off offset:16
	global_load_dwordx4 v[240:243], v[84:85], off
	s_waitcnt vmcnt(5)
	v_lshlrev_b32_e32 v104, 16, v72
	v_and_b32_e32 v105, 0xffff0000, v72
	v_mul_f32_e32 v8, 0xbfb8aa3b, v104
	v_exp_f32_e32 v8, v8
	v_mul_f32_e32 v72, 0xbfb8aa3b, v105
	v_exp_f32_e32 v106, v72
	v_and_b32_e32 v107, 0xffff0000, v73
	v_add_f32_e32 v8, 1.0, v8
	v_rcp_f32_e32 v72, v8
	v_add_f32_e32 v8, 1.0, v106
	v_lshlrev_b32_e32 v106, 16, v73
	v_mul_f32_e32 v73, 0xbfb8aa3b, v106
	v_exp_f32_e32 v108, v73
	v_mul_f32_e32 v73, 0xbfb8aa3b, v107
	v_exp_f32_e32 v109, v73
	v_lshlrev_b32_e32 v110, 16, v74
	v_rcp_f32_e32 v73, v8
	v_add_f32_e32 v8, 1.0, v108
	v_and_b32_e32 v111, 0xffff0000, v74
	v_mul_f32_e32 v74, 0xbfb8aa3b, v110
	v_rcp_f32_e32 v108, v8
	v_add_f32_e32 v8, 1.0, v109
	v_exp_f32_e32 v74, v74
	v_mul_f32_e32 v109, 0xbfb8aa3b, v111
	v_exp_f32_e32 v112, v109
	v_rcp_f32_e32 v109, v8
	v_add_f32_e32 v8, 1.0, v74
	v_rcp_f32_e32 v74, v8
	v_add_f32_e32 v8, 1.0, v112
	v_lshlrev_b32_e32 v112, 16, v75
	v_and_b32_e32 v113, 0xffff0000, v75
	v_mul_f32_e32 v75, 0xbfb8aa3b, v112
	v_exp_f32_e32 v114, v75
	v_mul_f32_e32 v75, 0xbfb8aa3b, v113
	v_exp_f32_e32 v115, v75
	v_rcp_f32_e32 v75, v8
	v_add_f32_e32 v8, 1.0, v114
	v_rcp_f32_e32 v114, v8
	v_add_f32_e32 v8, 1.0, v115
	v_rcp_f32_e32 v115, v8
	v_lshl_add_u32 v8, v129, 2, s96
	v_pk_mul_f32 v[106:107], v[108:109], v[106:107]
	v_pk_mul_f32 v[108:109], v[74:75], v[110:111]
	ds_read2st64_b32 v[74:75], v8 offset1:1
	v_pk_mul_f32 v[110:111], v[114:115], v[112:113]
	ds_read2st64_b32 v[112:113], v8 offset0:2 offset1:3
	ds_read2st64_b32 v[114:115], v8 offset0:4 offset1:5
	ds_read2st64_b32 v[116:117], v8 offset0:6 offset1:7
	s_waitcnt lgkmcnt(7)
	v_mov_b32_e32 v119, v94
	v_lshlrev_b64 v[102:103], 11, v[124:125]
	s_waitcnt lgkmcnt(3)
	v_mov_b32_e32 v118, v74
	v_pk_add_f32 v[118:119], v[118:119], 0 op_sel_hi:[1,0]
	v_mov_b32_e32 v94, v75
	v_pk_add_f32 v[74:75], v[118:119], v[94:95]
	s_waitcnt lgkmcnt(2)
	v_mov_b32_e32 v94, v112
	v_mov_b32_e32 v95, v96
	v_pk_add_f32 v[74:75], v[74:75], v[94:95]
	v_mov_b32_e32 v96, v113
	v_pk_add_f32 v[74:75], v[74:75], v[96:97]
	s_waitcnt lgkmcnt(1)
	v_mov_b32_e32 v94, v114
	v_mov_b32_e32 v95, v98
	v_pk_add_f32 v[74:75], v[74:75], v[94:95]
	v_mov_b32_e32 v98, v115
	v_pk_add_f32 v[74:75], v[74:75], v[98:99]
	s_waitcnt lgkmcnt(0)
	v_mov_b32_e32 v94, v116
	v_mov_b32_e32 v95, v100
	v_pk_add_f32 v[74:75], v[74:75], v[94:95]
	v_mov_b32_e32 v100, v117
	v_pk_add_f32 v[94:95], v[74:75], v[100:101]
	v_mov_b64_e32 v[74:75], s[48:49]
	v_pk_fma_f32 v[94:95], v[94:95], s[46:47], v[74:75] op_sel_hi:[1,0,0]
	v_ashrrev_i32_e32 v133, 31, v132
	v_mul_f32_e32 v8, 0x4b800000, v95
	v_cmp_gt_f32_e32 vcc, s45, v95
	v_lshl_add_u64 v[102:103], s[28:29], 0, v[102:103]
	s_lshl_b32 s38, s2, 1
	v_cndmask_b32_e32 v8, v95, v8, vcc
	v_rsq_f32_e32 v8, v8
	v_pk_mul_f32 v[104:105], v[72:73], v[104:105]
	v_lshl_add_u64 v[102:103], v[102:103], 0, s[38:39]
	v_lshlrev_b64 v[72:73], 1, v[132:133]
	v_mul_f32_e32 v95, 0x45800000, v8
	v_cndmask_b32_e32 v8, v8, v95, vcc
	v_pk_mul_f32 v[80:81], v[80:81], v[8:9] op_sel_hi:[1,0]
	v_pk_mul_f32 v[82:83], v[82:83], v[8:9] op_sel_hi:[1,0]
	v_pk_mul_f32 v[76:77], v[76:77], v[8:9] op_sel_hi:[1,0]
	v_pk_mul_f32 v[78:79], v[78:79], v[8:9] op_sel_hi:[1,0]
	s_waitcnt vmcnt(0)
	v_pk_mul_f32 v[80:81], v[240:241], v[80:81]
	v_pk_mul_f32 v[82:83], v[242:243], v[82:83]
	v_pk_mul_f32 v[76:77], v[244:245], v[76:77]
	v_pk_mul_f32 v[78:79], v[246:247], v[78:79]
	v_lshl_add_u64 v[96:97], v[102:103], 0, v[72:73]
	v_mov_b32_e32 v127, v9
	v_pk_mul_f32 v[80:81], v[104:105], v[80:81]
	v_pk_mul_f32 v[82:83], v[106:107], v[82:83]
	v_pk_mul_f32 v[76:77], v[108:109], v[76:77]
	v_pk_mul_f32 v[78:79], v[110:111], v[78:79]
	v_lshl_add_u64 v[96:97], v[96:97], 0, v[126:127]
	v_cvt_pk_bf16_f32 v80, v80, v81
	v_cvt_pk_bf16_f32 v81, v82, v83
	v_cvt_pk_bf16_f32 v82, v76, v77
	v_cvt_pk_bf16_f32 v83, v78, v79
	global_store_dwordx4 v[96:97], v[80:83], off
	s_nop 1
	s_nop 0
	s_nop 0
	s_nop 0
	v_lshlrev_b32_e32 v86, 16, v68
	v_and_b32_e32 v87, 0xffff0000, v68
	v_lshlrev_b32_e32 v68, 16, v69
	v_mul_f32_e32 v8, 0xbfb8aa3b, v86
	v_mul_f32_e32 v92, 0xbfb8aa3b, v68
	v_exp_f32_e32 v8, v8
	v_exp_f32_e32 v92, v92
	v_and_b32_e32 v69, 0xffff0000, v69
	v_lshlrev_b32_e32 v88, 16, v70
	v_and_b32_e32 v89, 0xffff0000, v70
	v_mul_f32_e32 v70, 0xbfb8aa3b, v87
	v_mul_f32_e32 v93, 0xbfb8aa3b, v69
	v_add_f32_e32 v8, 1.0, v8
	v_mul_f32_e32 v96, 0xbfb8aa3b, v89
	v_exp_f32_e32 v70, v70
	v_exp_f32_e32 v93, v93
	v_add_f32_e32 v97, 1.0, v92
	v_rcp_f32_e32 v92, v8
	v_mul_f32_e32 v8, 0x4b800000, v94
	v_cmp_gt_f32_e32 vcc, s45, v94
	v_exp_f32_e32 v96, v96
	v_add_f32_e32 v70, 1.0, v70
	v_cndmask_b32_e32 v8, v94, v8, vcc
	v_rsq_f32_e32 v8, v8
	v_add_f32_e32 v98, 1.0, v93
	v_add_f32_e32 v99, 1.0, v96
	v_rcp_f32_e32 v93, v70
	v_rcp_f32_e32 v96, v97
	v_rcp_f32_e32 v97, v98
	v_mul_f32_e32 v70, 0x45800000, v8
	v_cndmask_b32_e32 v8, v8, v70, vcc
	v_pk_mul_f32 v[64:65], v[64:65], v[8:9] op_sel_hi:[1,0]
	v_pk_mul_f32 v[66:67], v[66:67], v[8:9] op_sel_hi:[1,0]
	v_pk_mul_f32 v[86:87], v[92:93], v[86:87]
	v_pk_mul_f32 v[68:69], v[96:97], v[68:69]
	v_pk_mul_f32 v[60:61], v[60:61], v[8:9] op_sel_hi:[1,0]
	v_mul_f32_e32 v95, 0xbfb8aa3b, v88
	v_exp_f32_e32 v95, v95
	v_rcp_f32_e32 v99, v99
	v_mov_b32_e32 v131, v125
	v_pk_mul_f32 v[62:63], v[62:63], v[8:9] op_sel_hi:[1,0]
	v_add_f32_e32 v95, 1.0, v95
	v_rcp_f32_e32 v98, v95
	v_lshlrev_b64 v[90:91], 11, v[130:131]
	v_lshl_add_u64 v[90:91], s[28:29], 0, v[90:91]
	v_lshl_add_u32 v8, v177, 2, s96
	v_mov_b32_e32 v129, v125
	s_cmpk_gt_i32 s47, 0x3ff
	s_mov_b64 s[8:9], -1
	s_nop 0
	v_pk_mul_f32 v[64:65], v[240:241], v[64:65]
	v_pk_mul_f32 v[66:67], v[242:243], v[66:67]
	s_nop 0
	v_pk_mul_f32 v[76:77], v[244:245], v[60:61]
	v_pk_mul_f32 v[60:61], v[86:87], v[64:65]
	v_pk_mul_f32 v[64:65], v[68:69], v[66:67]
	v_cvt_pk_bf16_f32 v60, v60, v61
	v_cvt_pk_bf16_f32 v61, v64, v65
	v_lshlrev_b32_e32 v64, 16, v71
	v_and_b32_e32 v65, 0xffff0000, v71
	v_mul_f32_e32 v66, 0xbfb8aa3b, v64
	v_exp_f32_e32 v68, v66
	v_mul_f32_e32 v66, 0xbfb8aa3b, v65
	v_exp_f32_e32 v69, v66
	v_pk_mul_f32 v[62:63], v[246:247], v[62:63]
	v_add_f32_e32 v68, 1.0, v68
	v_rcp_f32_e32 v68, v68
	v_add_f32_e32 v69, 1.0, v69
	v_rcp_f32_e32 v69, v69
	v_pk_mul_f32 v[66:67], v[98:99], v[88:89]
	v_lshlrev_b32_e32 v82, 16, v56
	v_pk_mul_f32 v[66:67], v[66:67], v[76:77]
	v_pk_mul_f32 v[64:65], v[68:69], v[64:65]
	v_and_b32_e32 v83, 0xffff0000, v56
	v_pk_mul_f32 v[64:65], v[64:65], v[62:63]
	v_cvt_pk_bf16_f32 v62, v66, v67
	v_cvt_pk_bf16_f32 v63, v64, v65
	v_lshl_add_u64 v[64:65], v[90:91], 0, s[38:39]
	v_lshl_add_u64 v[64:65], v[64:65], 0, v[72:73]
	v_lshl_add_u64 v[64:65], v[64:65], 0, v[126:127]
	global_store_dwordx4 v[64:65], v[60:63], off
	s_nop 1
	ds_read2st64_b32 v[68:69], v8 offset1:1
	ds_read2st64_b32 v[70:71], v8 offset0:2 offset1:3
	ds_read2st64_b32 v[76:77], v8 offset0:4 offset1:5
	ds_read2st64_b32 v[78:79], v8 offset0:6 offset1:7
	s_nop 0
	s_nop 0
	v_mul_f32_e32 v8, 0xbfb8aa3b, v82
	v_exp_f32_e32 v8, v8
	v_mul_f32_e32 v56, 0xbfb8aa3b, v83
	v_exp_f32_e32 v56, v56
	v_and_b32_e32 v89, 0xffff0000, v58
	v_add_f32_e32 v8, 1.0, v8
	v_rcp_f32_e32 v86, v8
	v_add_f32_e32 v8, 1.0, v56
	v_lshlrev_b32_e32 v56, 16, v57
	v_rcp_f32_e32 v87, v8
	v_and_b32_e32 v57, 0xffff0000, v57
	v_mul_f32_e32 v8, 0xbfb8aa3b, v56
	v_exp_f32_e32 v8, v8
	v_mul_f32_e32 v88, 0xbfb8aa3b, v57
	v_exp_f32_e32 v88, v88
	v_pk_mul_f32 v[82:83], v[86:87], v[82:83]
	v_add_f32_e32 v8, 1.0, v8
	v_rcp_f32_e32 v86, v8
	v_add_f32_e32 v8, 1.0, v88
	v_lshlrev_b32_e32 v88, 16, v58
	v_rcp_f32_e32 v87, v8
	v_mul_f32_e32 v8, 0xbfb8aa3b, v88
	v_exp_f32_e32 v8, v8
	v_mul_f32_e32 v58, 0xbfb8aa3b, v89
	v_exp_f32_e32 v90, v58
	v_pk_mul_f32 v[56:57], v[86:87], v[56:57]
	v_lshlrev_b32_e32 v86, 16, v59
	v_add_f32_e32 v8, 1.0, v8
	v_and_b32_e32 v87, 0xffff0000, v59
	v_mul_f32_e32 v59, 0xbfb8aa3b, v86
	v_rcp_f32_e32 v58, v8
	v_add_f32_e32 v8, 1.0, v90
	v_exp_f32_e32 v90, v59
	v_mul_f32_e32 v59, 0xbfb8aa3b, v87
	v_exp_f32_e32 v91, v59
	v_rcp_f32_e32 v59, v8
	v_add_f32_e32 v8, 1.0, v90
	v_rcp_f32_e32 v90, v8
	v_add_f32_e32 v8, 1.0, v91
	v_rcp_f32_e32 v91, v8
	v_lshl_add_u32 v8, v11, 2, s96
	v_pk_mul_f32 v[58:59], v[58:59], v[88:89]
	ds_read2st64_b32 v[88:89], v8 offset1:1
	v_pk_mul_f32 v[86:87], v[90:91], v[86:87]
	ds_read2st64_b32 v[90:91], v8 offset0:2 offset1:3
	ds_read2st64_b32 v[92:93], v8 offset0:4 offset1:5
	ds_read2st64_b32 v[94:95], v8 offset0:6 offset1:7
	s_waitcnt lgkmcnt(7)
	v_mov_b32_e32 v97, v68
	v_lshlrev_b64 v[80:81], 11, v[128:129]
	s_waitcnt lgkmcnt(3)
	v_mov_b32_e32 v96, v88
	v_pk_add_f32 v[96:97], v[96:97], 0 op_sel_hi:[1,0]
	v_mov_b32_e32 v68, v89
	v_pk_add_f32 v[68:69], v[96:97], v[68:69]
	s_waitcnt lgkmcnt(2)
	v_mov_b32_e32 v88, v90
	v_mov_b32_e32 v89, v70
	v_pk_add_f32 v[68:69], v[68:69], v[88:89]
	v_mov_b32_e32 v70, v91
	v_pk_add_f32 v[68:69], v[68:69], v[70:71]
	s_waitcnt lgkmcnt(1)
	v_mov_b32_e32 v70, v92
	v_mov_b32_e32 v71, v76
	v_pk_add_f32 v[68:69], v[68:69], v[70:71]
	v_mov_b32_e32 v76, v93
	v_pk_add_f32 v[68:69], v[68:69], v[76:77]
	s_waitcnt lgkmcnt(0)
	v_mov_b32_e32 v70, v94
	v_mov_b32_e32 v71, v78
	v_pk_add_f32 v[68:69], v[68:69], v[70:71]
	v_mov_b32_e32 v78, v95
	v_pk_add_f32 v[68:69], v[68:69], v[78:79]
	v_lshl_add_u64 v[80:81], s[28:29], 0, v[80:81]
	v_pk_fma_f32 v[68:69], v[68:69], s[46:47], v[74:75] op_sel_hi:[1,0,0]
	v_lshl_add_u64 v[70:71], v[80:81], 0, s[38:39]
	v_mul_f32_e32 v8, 0x4b800000, v69
	v_cmp_gt_f32_e32 vcc, s45, v69
	v_lshl_add_u64 v[70:71], v[70:71], 0, v[72:73]
	v_lshl_add_u64 v[70:71], v[70:71], 0, v[126:127]
	v_cndmask_b32_e32 v8, v69, v8, vcc
	v_rsq_f32_e32 v8, v8
	s_nop 0
	v_mul_f32_e32 v11, 0x45800000, v8
	v_cndmask_b32_e32 v8, v8, v11, vcc
	v_pk_mul_f32 v[52:53], v[52:53], v[8:9] op_sel_hi:[1,0]
	v_pk_mul_f32 v[54:55], v[54:55], v[8:9] op_sel_hi:[1,0]
	v_pk_mul_f32 v[48:49], v[48:49], v[8:9] op_sel_hi:[1,0]
	v_pk_mul_f32 v[50:51], v[50:51], v[8:9] op_sel_hi:[1,0]
	s_nop 0
	v_pk_mul_f32 v[52:53], v[240:241], v[52:53]
	v_pk_mul_f32 v[54:55], v[242:243], v[54:55]
	v_pk_mul_f32 v[48:49], v[244:245], v[48:49]
	v_pk_mul_f32 v[50:51], v[246:247], v[50:51]
	v_pk_mul_f32 v[52:53], v[82:83], v[52:53]
	v_pk_mul_f32 v[54:55], v[56:57], v[54:55]
	v_pk_mul_f32 v[48:49], v[58:59], v[48:49]
	v_pk_mul_f32 v[50:51], v[86:87], v[50:51]
	v_cvt_pk_bf16_f32 v52, v52, v53
	v_cvt_pk_bf16_f32 v53, v54, v55
	v_cvt_pk_bf16_f32 v54, v48, v49
	v_cvt_pk_bf16_f32 v55, v50, v51
	global_store_dwordx4 v[70:71], v[52:55], off
	s_nop 1
	s_nop 0
	s_nop 0
	s_nop 0
	v_lshlrev_b32_e32 v56, 16, v44
	v_and_b32_e32 v57, 0xffff0000, v44
	v_lshlrev_b32_e32 v44, 16, v45
	v_mul_f32_e32 v8, 0xbfb8aa3b, v56
	v_mul_f32_e32 v60, 0xbfb8aa3b, v44
	v_exp_f32_e32 v8, v8
	v_exp_f32_e32 v60, v60
	v_and_b32_e32 v45, 0xffff0000, v45
	v_mul_f32_e32 v61, 0xbfb8aa3b, v45
	v_add_f32_e32 v8, 1.0, v8
	v_mul_f32_e32 v59, 0xbfb8aa3b, v57
	v_exp_f32_e32 v61, v61
	v_add_f32_e32 v62, 1.0, v60
	v_rcp_f32_e32 v60, v8
	v_mul_f32_e32 v8, 0x4b800000, v68
	v_cmp_gt_f32_e32 vcc, s45, v68
	v_exp_f32_e32 v59, v59
	v_add_f32_e32 v63, 1.0, v61
	v_cndmask_b32_e32 v8, v68, v8, vcc
	v_rsq_f32_e32 v8, v8
	v_add_f32_e32 v59, 1.0, v59
	v_rcp_f32_e32 v62, v62
	v_rcp_f32_e32 v63, v63
	v_rcp_f32_e32 v61, v59
	v_mul_f32_e32 v59, 0x45800000, v8
	v_cndmask_b32_e32 v8, v8, v59, vcc
	v_pk_mul_f32 v[42:43], v[42:43], v[8:9] op_sel_hi:[1,0]
	v_lshlrev_b32_e32 v58, 16, v46
	v_pk_mul_f32 v[44:45], v[62:63], v[44:45]
	v_pk_mul_f32 v[40:41], v[40:41], v[8:9] op_sel_hi:[1,0]
	v_pk_mul_f32 v[56:57], v[60:61], v[56:57]
	v_and_b32_e32 v59, 0xffff0000, v46
	v_mov_b32_e32 v11, v125
	v_lshlrev_b64 v[10:11], 11, v[10:11]
	v_pk_mul_f32 v[36:37], v[36:37], v[8:9] op_sel_hi:[1,0]
	v_lshl_add_u64 v[10:11], s[28:29], 0, v[10:11]
	v_pk_mul_f32 v[38:39], v[38:39], v[8:9] op_sel_hi:[1,0]
	v_lshl_add_u64 v[10:11], v[10:11], 0, s[38:39]
	v_lshl_add_u64 v[10:11], v[10:11], 0, v[72:73]
	v_lshl_add_u64 v[10:11], v[10:11], 0, v[126:127]
	s_nop 0
	v_pk_mul_f32 v[42:43], v[242:243], v[42:43]
	s_nop 0
	v_pk_mul_f32 v[42:43], v[44:45], v[42:43]
	v_mul_f32_e32 v44, 0xbfb8aa3b, v58
	v_exp_f32_e32 v44, v44
	v_pk_mul_f32 v[40:41], v[240:241], v[40:41]
	v_and_b32_e32 v45, 0xffff0000, v47
	v_pk_mul_f32 v[40:41], v[56:57], v[40:41]
	s_nop 0
	v_pk_mul_f32 v[36:37], v[244:245], v[36:37]
	v_cvt_pk_bf16_f32 v40, v40, v41
	v_cvt_pk_bf16_f32 v41, v42, v43
	v_add_f32_e32 v42, 1.0, v44
	v_mul_f32_e32 v43, 0xbfb8aa3b, v59
	v_lshlrev_b32_e32 v44, 16, v47
	v_exp_f32_e32 v43, v43
	v_mul_f32_e32 v46, 0xbfb8aa3b, v44
	v_mul_f32_e32 v47, 0xbfb8aa3b, v45
	v_exp_f32_e32 v46, v46
	v_exp_f32_e32 v47, v47
	v_add_f32_e32 v43, 1.0, v43
	v_rcp_f32_e32 v42, v42
	v_rcp_f32_e32 v43, v43
	v_add_f32_e32 v46, 1.0, v46
	v_add_f32_e32 v47, 1.0, v47
	v_rcp_f32_e32 v46, v46
	v_rcp_f32_e32 v47, v47
	v_pk_mul_f32 v[42:43], v[42:43], v[58:59]
	v_pk_mul_f32 v[38:39], v[246:247], v[38:39]
	v_pk_mul_f32 v[36:37], v[42:43], v[36:37]
	v_pk_mul_f32 v[42:43], v[46:47], v[44:45]
	s_nop 0
	v_pk_mul_f32 v[38:39], v[42:43], v[38:39]
	v_cvt_pk_bf16_f32 v42, v36, v37
	v_cvt_pk_bf16_f32 v43, v38, v39
	global_store_dwordx4 v[10:11], v[40:43], off
	s_nop 1
	s_barrier
	s_cbranch_scc1 .LBB0_1738
	s_add_i32 s2, s89, s49
	s_cmpk_gt_i32 s2, 0x3ff
	s_cbranch_scc1 .LBB0_1780
	v_mov_b32_e32 v8, v204
	s_ashr_i32 s8, s2, 8
	s_ashr_i32 s9, s8, 31
	v_ashrrev_i32_e32 v0, 31, v8
	s_add_i32 s2, s88, s3
	v_lshrrev_b32_e32 v0, 27, v0
	s_lshl_b64 s[8:9], s[8:9], 12
	s_and_b32 s2, s2, 0xfc0
	v_add_u32_e32 v1, v8, v0
	s_or_b32 s2, s8, s2
	v_ashrrev_i32_e32 v0, 5, v1
	v_and_b32_e32 v1, 0x1fffffe0, v1
	s_add_u32 s8, s2, 0x4000
	v_sub_u32_e32 v1, v8, v1
	s_addc_u32 s9, s9, 0
	v_lshlrev_b32_e32 v2, 3, v1
	v_ashrrev_i32_e32 v1, 31, v0
	v_add_u32_e32 v13, 0x400, v8
	s_add_i32 s2, s83, s72
	v_lshl_add_u64 v[0:1], s[8:9], 0, v[0:1]
	v_mov_b64_e32 v[10:11], s[30:31]
	v_ashrrev_i32_e32 v12, 31, v13
	s_and_b32 s2, s2, 0x300
	v_mad_u64_u32 v[4:5], s[10:11], v0, s0, v[10:11]
	v_lshrrev_b32_e32 v12, 27, v12
	v_mad_i32_i24 v5, v1, s0, v5
	s_lshl_b32 s38, s2, 1
	v_add_u32_e32 v14, v13, v12
	v_lshl_add_u64 v[0:1], v[4:5], 0, s[38:39]
	v_ashrrev_i32_e32 v3, 31, v2
	v_ashrrev_i32_e32 v12, 5, v14
	v_and_b32_e32 v14, 0x1fffffe0, v14
	v_lshl_add_u64 v[0:1], v[2:3], 1, v[0:1]
	v_add_u32_e32 v3, 0x200, v8
	v_sub_u32_e32 v13, v13, v14
	v_ashrrev_i32_e32 v2, 31, v3
	v_lshlrev_b32_e32 v14, 3, v13
	v_ashrrev_i32_e32 v13, 31, v12
	v_lshrrev_b32_e32 v2, 27, v2
	v_lshl_add_u64 v[12:13], s[8:9], 0, v[12:13]
	v_add_u32_e32 v4, v3, v2
	v_mad_u64_u32 v[16:17], s[10:11], v12, s0, v[10:11]
	v_ashrrev_i32_e32 v2, 5, v4
	v_and_b32_e32 v4, 0x1fffffe0, v4
	v_mad_i32_i24 v17, v13, s0, v17
	v_sub_u32_e32 v3, v3, v4
	v_lshl_add_u64 v[12:13], v[16:17], 0, s[38:39]
	v_ashrrev_i32_e32 v15, 31, v14
	v_add_u32_e32 v8, 0x600, v8
	v_lshlrev_b32_e32 v4, 3, v3
	v_ashrrev_i32_e32 v3, 31, v2
	v_lshl_add_u64 v[12:13], v[14:15], 1, v[12:13]
	v_ashrrev_i32_e32 v14, 31, v8
	v_lshl_add_u64 v[2:3], s[8:9], 0, v[2:3]
	v_lshrrev_b32_e32 v14, 27, v14
	v_mad_u64_u32 v[6:7], s[10:11], v2, s0, v[10:11]
	v_add_u32_e32 v15, v8, v14
	v_mad_i32_i24 v7, v3, s0, v7
	v_ashrrev_i32_e32 v14, 5, v15
	v_and_b32_e32 v15, 0x1fffffe0, v15
	v_add_co_u32_e32 v0, vcc, s1, v0
	v_lshl_add_u64 v[2:3], v[6:7], 0, s[38:39]
	v_ashrrev_i32_e32 v5, 31, v4
	v_sub_u32_e32 v8, v8, v15
	v_ashrrev_i32_e32 v15, 31, v14
	v_addc_co_u32_e32 v1, vcc, 0, v1, vcc
	v_lshl_add_u64 v[2:3], v[4:5], 1, v[2:3]
	v_lshl_add_u64 v[14:15], s[8:9], 0, v[14:15]
	v_add_co_u32_e32 v4, vcc, s1, v2
	v_mad_u64_u32 v[10:11], s[8:9], v14, s0, v[10:11]
	s_nop 0
	v_addc_co_u32_e32 v5, vcc, 0, v3, vcc
	v_lshlrev_b32_e32 v16, 3, v8
	v_mad_i32_i24 v11, v15, s0, v11
	v_add_co_u32_e32 v12, vcc, s1, v12
	v_lshl_add_u64 v[10:11], v[10:11], 0, s[38:39]
	v_ashrrev_i32_e32 v17, 31, v16
	v_addc_co_u32_e32 v13, vcc, 0, v13, vcc
	v_lshl_add_u64 v[10:11], v[16:17], 1, v[10:11]
	v_add_co_u32_e32 v10, vcc, 0x7a00000, v10
	global_load_dwordx4 v[0:3], v[0:1], off offset:2048
	s_nop 0
	global_load_dwordx4 v[4:7], v[4:5], off offset:2048
	v_addc_co_u32_e32 v11, vcc, 0, v11, vcc
	global_load_dwordx4 v[12:15], v[12:13], off offset:2048
	s_nop 0
	global_load_dwordx4 v[16:19], v[10:11], off offset:2048

.LBB0_1893:
	s_ashr_i32 s29, s28, 31
	v_cmp_lt_i64_e32 vcc, s[30:31], v[164:165]
	s_lshl_b64 s[30:31], s[28:29], 19
	s_add_u32 s30, s12, s30
	s_addc_u32 s31, s13, s31
	s_and_b64 s[34:35], vcc, exec
	s_cselect_b32 s29, s31, s41
	s_cselect_b32 s37, s30, s40
	s_ashr_i32 s27, s26, 31
	s_lshl_b64 s[34:35], s[26:27], 19
	s_add_u32 s34, s1, s34
	s_addc_u32 s35, s2, s35
	s_and_b64 s[44:45], vcc, exec
	s_cselect_b32 s27, s35, s43
	s_cselect_b32 s54, s34, s42
	s_add_u32 s40, s40, 0x40080
	s_addc_u32 s41, s41, 0
	s_add_u32 s55, s42, 0x100
	v_mov_b32_e32 v0, 0
	s_addc_u32 s56, s43, 0
	s_mov_b32 s57, -2
	s_waitcnt lgkmcnt(0)
	v_mov_b32_e32 v1, v0
	v_mov_b32_e32 v2, v0
	v_mov_b32_e32 v3, v0
	v_mov_b32_e32 v4, v0
	v_mov_b32_e32 v5, v0
	v_mov_b32_e32 v6, v0
	v_mov_b32_e32 v7, v0

	v_mov_b32_e32 v16, v0
	v_mov_b32_e32 v17, v0
	v_mov_b32_e32 v18, v0
	v_mov_b32_e32 v19, v0
	v_mov_b32_e32 v20, v0
	v_mov_b32_e32 v21, v0
	v_mov_b32_e32 v22, v0
	v_mov_b32_e32 v23, v0
	v_mov_b32_e32 v32, v0
	v_mov_b32_e32 v33, v0
	v_mov_b32_e32 v34, v0
	v_mov_b32_e32 v35, v0
	v_mov_b32_e32 v36, v0
	v_mov_b32_e32 v37, v0
	v_mov_b32_e32 v38, v0
	v_mov_b32_e32 v39, v0
	v_mov_b32_e32 v48, v0
	v_mov_b32_e32 v49, v0
	v_mov_b32_e32 v50, v0
	v_mov_b32_e32 v51, v0
	v_mov_b32_e32 v52, v0
	v_mov_b32_e32 v53, v0
	v_mov_b32_e32 v54, v0
	v_mov_b32_e32 v55, v0
	v_mov_b32_e32 v8, v0
	v_mov_b32_e32 v9, v0
	v_mov_b32_e32 v10, v0
	v_mov_b32_e32 v11, v0
	v_mov_b32_e32 v12, v0
	v_mov_b32_e32 v13, v0
	v_mov_b32_e32 v14, v0
	v_mov_b32_e32 v15, v0
	v_mov_b32_e32 v24, v0
	v_mov_b32_e32 v25, v0
	v_mov_b32_e32 v26, v0
	v_mov_b32_e32 v27, v0
	v_mov_b32_e32 v28, v0
	v_mov_b32_e32 v29, v0
	v_mov_b32_e32 v30, v0
	v_mov_b32_e32 v31, v0
	v_mov_b32_e32 v40, v0
	v_mov_b32_e32 v41, v0
	v_mov_b32_e32 v42, v0
	v_mov_b32_e32 v43, v0
	v_mov_b32_e32 v44, v0
	v_mov_b32_e32 v45, v0
	v_mov_b32_e32 v46, v0
	v_mov_b32_e32 v47, v0
	v_mov_b32_e32 v56, v0
	v_mov_b32_e32 v57, v0
	v_mov_b32_e32 v58, v0
	v_mov_b32_e32 v59, v0
	v_mov_b32_e32 v60, v0
	v_mov_b32_e32 v61, v0
	v_mov_b32_e32 v62, v0
	v_mov_b32_e32 v63, v0
	v_mov_b32_e32 v64, v0
	v_mov_b32_e32 v65, v0
	v_mov_b32_e32 v66, v0
	v_mov_b32_e32 v67, v0
	v_mov_b32_e32 v68, v0
	v_mov_b32_e32 v69, v0
	v_mov_b32_e32 v70, v0
	v_mov_b32_e32 v71, v0
	v_mov_b32_e32 v80, v0
	v_mov_b32_e32 v81, v0
	v_mov_b32_e32 v82, v0
	v_mov_b32_e32 v83, v0
	v_mov_b32_e32 v84, v0
	v_mov_b32_e32 v85, v0
	v_mov_b32_e32 v86, v0
	v_mov_b32_e32 v87, v0
	v_mov_b32_e32 v96, v0
	v_mov_b32_e32 v97, v0
	v_mov_b32_e32 v98, v0
	v_mov_b32_e32 v99, v0
	v_mov_b32_e32 v100, v0
	v_mov_b32_e32 v101, v0
	v_mov_b32_e32 v102, v0
	v_mov_b32_e32 v103, v0
	v_mov_b32_e32 v112, v0
	v_mov_b32_e32 v113, v0
	v_mov_b32_e32 v114, v0
	v_mov_b32_e32 v115, v0
	v_mov_b32_e32 v116, v0
	v_mov_b32_e32 v117, v0
	v_mov_b32_e32 v118, v0
	v_mov_b32_e32 v119, v0
	v_mov_b32_e32 v72, v0
	v_mov_b32_e32 v73, v0
	v_mov_b32_e32 v74, v0
	v_mov_b32_e32 v75, v0
	v_mov_b32_e32 v76, v0
	v_mov_b32_e32 v77, v0
	v_mov_b32_e32 v78, v0
	v_mov_b32_e32 v79, v0
	v_mov_b32_e32 v88, v0
	v_mov_b32_e32 v89, v0
	v_mov_b32_e32 v90, v0
	v_mov_b32_e32 v91, v0
	v_mov_b32_e32 v92, v0
	v_mov_b32_e32 v93, v0
	v_mov_b32_e32 v94, v0
	v_mov_b32_e32 v95, v0
	v_mov_b32_e32 v104, v0
	v_mov_b32_e32 v105, v0
	v_mov_b32_e32 v106, v0
	v_mov_b32_e32 v107, v0
	v_mov_b32_e32 v108, v0
	v_mov_b32_e32 v109, v0
	v_mov_b32_e32 v110, v0
	v_mov_b32_e32 v111, v0
	v_mov_b32_e32 v120, v0
	v_mov_b32_e32 v121, v0
	v_mov_b32_e32 v122, v0
	v_mov_b32_e32 v123, v0
	v_mov_b32_e32 v124, v0
	v_mov_b32_e32 v125, v0
	v_mov_b32_e32 v126, v0
	v_mov_b32_e32 v127, v0

.LBB0_1980:
	s_ashr_i32 s37, s36, 31
	v_cmp_lt_i64_e32 vcc, s[38:39], v[140:141]
	s_lshl_b64 s[38:39], s[36:37], 19
	s_add_u32 s38, s2, s38
	s_addc_u32 s39, s3, s39
	s_and_b64 s[40:41], vcc, exec
	s_cselect_b32 s9, s39, s11
	s_cselect_b32 s37, s38, s10
	s_ashr_i32 s35, s34, 31
	s_lshl_b64 s[40:41], s[34:35], 19
	s_add_u32 s40, s20, s40
	s_addc_u32 s41, s21, s41
	s_and_b64 s[44:45], vcc, exec
	s_cselect_b32 s35, s41, s43
	s_cselect_b32 s63, s40, s42
	s_add_u32 s10, s10, 0x40080
	s_addc_u32 s11, s11, 0
	s_add_u32 s64, s42, 0x100
	v_mov_b32_e32 v0, 0
	s_addc_u32 s65, s43, 0
	s_mov_b32 s66, -2
	v_mov_b32_e32 v1, v0
	v_mov_b32_e32 v2, v0
	v_mov_b32_e32 v3, v0
	v_mov_b32_e32 v4, v0
	v_mov_b32_e32 v5, v0
	v_mov_b32_e32 v6, v0
	v_mov_b32_e32 v7, v0

	v_mov_b32_e32 v16, v0
	v_mov_b32_e32 v17, v0
	v_mov_b32_e32 v18, v0
	v_mov_b32_e32 v19, v0
	v_mov_b32_e32 v20, v0
	v_mov_b32_e32 v21, v0
	v_mov_b32_e32 v22, v0
	v_mov_b32_e32 v23, v0
	v_mov_b32_e32 v32, v0
	v_mov_b32_e32 v33, v0
	v_mov_b32_e32 v34, v0
	v_mov_b32_e32 v35, v0
	v_mov_b32_e32 v36, v0
	v_mov_b32_e32 v37, v0
	v_mov_b32_e32 v38, v0
	v_mov_b32_e32 v39, v0
	v_mov_b32_e32 v48, v0
	v_mov_b32_e32 v49, v0
	v_mov_b32_e32 v50, v0
	v_mov_b32_e32 v51, v0
	v_mov_b32_e32 v52, v0
	v_mov_b32_e32 v53, v0
	v_mov_b32_e32 v54, v0
	v_mov_b32_e32 v55, v0
	v_mov_b32_e32 v8, v0
	v_mov_b32_e32 v9, v0
	v_mov_b32_e32 v10, v0
	v_mov_b32_e32 v11, v0
	v_mov_b32_e32 v12, v0
	v_mov_b32_e32 v13, v0
	v_mov_b32_e32 v14, v0
	v_mov_b32_e32 v15, v0
	v_mov_b32_e32 v24, v0
	v_mov_b32_e32 v25, v0
	v_mov_b32_e32 v26, v0
	v_mov_b32_e32 v27, v0
	v_mov_b32_e32 v28, v0
	v_mov_b32_e32 v29, v0
	v_mov_b32_e32 v30, v0
	v_mov_b32_e32 v31, v0
	v_mov_b32_e32 v40, v0
	v_mov_b32_e32 v41, v0
	v_mov_b32_e32 v42, v0
	v_mov_b32_e32 v43, v0
	v_mov_b32_e32 v44, v0
	v_mov_b32_e32 v45, v0
	v_mov_b32_e32 v46, v0
	v_mov_b32_e32 v47, v0
	v_mov_b32_e32 v56, v0
	v_mov_b32_e32 v57, v0
	v_mov_b32_e32 v58, v0
	v_mov_b32_e32 v59, v0
	v_mov_b32_e32 v60, v0
	v_mov_b32_e32 v61, v0
	v_mov_b32_e32 v62, v0
	v_mov_b32_e32 v63, v0
	v_mov_b32_e32 v64, v0
	v_mov_b32_e32 v65, v0
	v_mov_b32_e32 v66, v0
	v_mov_b32_e32 v67, v0
	v_mov_b32_e32 v68, v0
	v_mov_b32_e32 v69, v0
	v_mov_b32_e32 v70, v0
	v_mov_b32_e32 v71, v0
	v_mov_b32_e32 v80, v0
	v_mov_b32_e32 v81, v0
	v_mov_b32_e32 v82, v0
	v_mov_b32_e32 v83, v0
	v_mov_b32_e32 v84, v0
	v_mov_b32_e32 v85, v0
	v_mov_b32_e32 v86, v0
	v_mov_b32_e32 v87, v0
	v_mov_b32_e32 v96, v0
	v_mov_b32_e32 v97, v0
	v_mov_b32_e32 v98, v0
	v_mov_b32_e32 v99, v0
	v_mov_b32_e32 v100, v0
	v_mov_b32_e32 v101, v0
	v_mov_b32_e32 v102, v0
	v_mov_b32_e32 v103, v0
	v_mov_b32_e32 v112, v0
	v_mov_b32_e32 v113, v0
	v_mov_b32_e32 v114, v0
	v_mov_b32_e32 v115, v0
	v_mov_b32_e32 v116, v0
	v_mov_b32_e32 v117, v0
	v_mov_b32_e32 v118, v0
	v_mov_b32_e32 v119, v0
	v_mov_b32_e32 v72, v0
	v_mov_b32_e32 v73, v0
	v_mov_b32_e32 v74, v0
	v_mov_b32_e32 v75, v0
	v_mov_b32_e32 v76, v0
	v_mov_b32_e32 v77, v0
	v_mov_b32_e32 v78, v0
	v_mov_b32_e32 v79, v0
	v_mov_b32_e32 v88, v0
	v_mov_b32_e32 v89, v0
	v_mov_b32_e32 v90, v0
	v_mov_b32_e32 v91, v0
	v_mov_b32_e32 v92, v0
	v_mov_b32_e32 v93, v0
	v_mov_b32_e32 v94, v0
	v_mov_b32_e32 v95, v0
	v_mov_b32_e32 v104, v0
	v_mov_b32_e32 v105, v0
	v_mov_b32_e32 v106, v0
	v_mov_b32_e32 v107, v0
	v_mov_b32_e32 v108, v0
	v_mov_b32_e32 v109, v0
	v_mov_b32_e32 v110, v0
	v_mov_b32_e32 v111, v0
	v_mov_b32_e32 v120, v0
	v_mov_b32_e32 v121, v0
	v_mov_b32_e32 v122, v0
	v_mov_b32_e32 v123, v0
	v_mov_b32_e32 v124, v0
	v_mov_b32_e32 v125, v0
	v_mov_b32_e32 v126, v0
	v_mov_b32_e32 v127, v0

.LBB0_2055:
	s_ashr_i32 s19, s18, 31
	v_cmp_lt_i64_e32 vcc, s[24:25], v[164:165]
	s_lshl_b64 s[24:25], s[18:19], 21
	s_add_u32 s24, s1, s24
	s_addc_u32 s25, s2, s25
	s_and_b64 s[26:27], vcc, exec
	s_cselect_b32 s19, s25, s35
	s_cselect_b32 s29, s24, s34
	s_ashr_i32 s17, s16, 31
	s_lshl_b64 s[26:27], s[16:17], 21
	s_add_u32 s26, s3, s26
	s_addc_u32 s27, s20, s27
	s_and_b64 s[38:39], vcc, exec
	s_cselect_b32 s17, s27, s37
	s_cselect_b32 s50, s26, s36
	s_add_u32 s34, s34, 0x100080
	s_addc_u32 s35, s35, 0
	s_add_u32 s51, s36, 0x100
	v_mov_b32_e32 v0, 0
	s_addc_u32 s52, s37, 0
	s_mov_b32 s53, -2
	s_waitcnt lgkmcnt(0)
	v_mov_b32_e32 v1, v0
	v_mov_b32_e32 v2, v0
	v_mov_b32_e32 v3, v0
	v_mov_b32_e32 v4, v0
	v_mov_b32_e32 v5, v0
	v_mov_b32_e32 v6, v0
	v_mov_b32_e32 v7, v0

	v_mov_b32_e32 v16, v0
	v_mov_b32_e32 v17, v0
	v_mov_b32_e32 v18, v0
	v_mov_b32_e32 v19, v0
	v_mov_b32_e32 v20, v0
	v_mov_b32_e32 v21, v0
	v_mov_b32_e32 v22, v0
	v_mov_b32_e32 v23, v0
	v_mov_b32_e32 v32, v0
	v_mov_b32_e32 v33, v0
	v_mov_b32_e32 v34, v0
	v_mov_b32_e32 v35, v0
	v_mov_b32_e32 v36, v0
	v_mov_b32_e32 v37, v0
	v_mov_b32_e32 v38, v0
	v_mov_b32_e32 v39, v0
	v_mov_b32_e32 v48, v0
	v_mov_b32_e32 v49, v0
	v_mov_b32_e32 v50, v0
	v_mov_b32_e32 v51, v0
	v_mov_b32_e32 v52, v0
	v_mov_b32_e32 v53, v0
	v_mov_b32_e32 v54, v0
	v_mov_b32_e32 v55, v0
	v_mov_b32_e32 v8, v0
	v_mov_b32_e32 v9, v0
	v_mov_b32_e32 v10, v0
	v_mov_b32_e32 v11, v0
	v_mov_b32_e32 v12, v0
	v_mov_b32_e32 v13, v0
	v_mov_b32_e32 v14, v0
	v_mov_b32_e32 v15, v0
	v_mov_b32_e32 v24, v0
	v_mov_b32_e32 v25, v0
	v_mov_b32_e32 v26, v0
	v_mov_b32_e32 v27, v0
	v_mov_b32_e32 v28, v0
	v_mov_b32_e32 v29, v0
	v_mov_b32_e32 v30, v0
	v_mov_b32_e32 v31, v0
	v_mov_b32_e32 v40, v0
	v_mov_b32_e32 v41, v0
	v_mov_b32_e32 v42, v0
	v_mov_b32_e32 v43, v0
	v_mov_b32_e32 v44, v0
	v_mov_b32_e32 v45, v0
	v_mov_b32_e32 v46, v0
	v_mov_b32_e32 v47, v0
	v_mov_b32_e32 v56, v0
	v_mov_b32_e32 v57, v0
	v_mov_b32_e32 v58, v0
	v_mov_b32_e32 v59, v0
	v_mov_b32_e32 v60, v0
	v_mov_b32_e32 v61, v0
	v_mov_b32_e32 v62, v0
	v_mov_b32_e32 v63, v0
	v_mov_b32_e32 v64, v0
	v_mov_b32_e32 v65, v0
	v_mov_b32_e32 v66, v0
	v_mov_b32_e32 v67, v0
	v_mov_b32_e32 v68, v0
	v_mov_b32_e32 v69, v0
	v_mov_b32_e32 v70, v0
	v_mov_b32_e32 v71, v0
	v_mov_b32_e32 v80, v0
	v_mov_b32_e32 v81, v0
	v_mov_b32_e32 v82, v0
	v_mov_b32_e32 v83, v0
	v_mov_b32_e32 v84, v0
	v_mov_b32_e32 v85, v0
	v_mov_b32_e32 v86, v0
	v_mov_b32_e32 v87, v0
	v_mov_b32_e32 v96, v0
	v_mov_b32_e32 v97, v0
	v_mov_b32_e32 v98, v0
	v_mov_b32_e32 v99, v0
	v_mov_b32_e32 v100, v0
	v_mov_b32_e32 v101, v0
	v_mov_b32_e32 v102, v0
	v_mov_b32_e32 v103, v0
	v_mov_b32_e32 v112, v0
	v_mov_b32_e32 v113, v0
	v_mov_b32_e32 v114, v0
	v_mov_b32_e32 v115, v0
	v_mov_b32_e32 v116, v0
	v_mov_b32_e32 v117, v0
	v_mov_b32_e32 v118, v0
	v_mov_b32_e32 v119, v0
	v_mov_b32_e32 v72, v0
	v_mov_b32_e32 v73, v0
	v_mov_b32_e32 v74, v0
	v_mov_b32_e32 v75, v0
	v_mov_b32_e32 v76, v0
	v_mov_b32_e32 v77, v0
	v_mov_b32_e32 v78, v0
	v_mov_b32_e32 v79, v0
	v_mov_b32_e32 v88, v0
	v_mov_b32_e32 v89, v0
	v_mov_b32_e32 v90, v0
	v_mov_b32_e32 v91, v0
	v_mov_b32_e32 v92, v0
	v_mov_b32_e32 v93, v0
	v_mov_b32_e32 v94, v0
	v_mov_b32_e32 v95, v0
	v_mov_b32_e32 v104, v0
	v_mov_b32_e32 v105, v0
	v_mov_b32_e32 v106, v0
	v_mov_b32_e32 v107, v0
	v_mov_b32_e32 v108, v0
	v_mov_b32_e32 v109, v0
	v_mov_b32_e32 v110, v0
	v_mov_b32_e32 v111, v0
	v_mov_b32_e32 v120, v0
	v_mov_b32_e32 v121, v0
	v_mov_b32_e32 v122, v0
	v_mov_b32_e32 v123, v0
	v_mov_b32_e32 v124, v0
	v_mov_b32_e32 v125, v0
	v_mov_b32_e32 v126, v0
	v_mov_b32_e32 v127, v0
